# all 7 GEMM K-loops: LDS-DMA staging 3/5/3/5 (only piece 1 of A[b][0] staged one phase later, SP2 waits vmcnt(7)); attention load hoist
# baseline (speedup 1.0000x reference)
; #define PG8_STAGE(bufoff, gbase, voff) do { _Pragma("unroll") for (int _i = 0; _i < 2; ++_i) \
;         __builtin_amdgcn_global_load_lds((const unsigned*)((const char*)(gbase) + (voff)[_i]), (LAS unsigned*)(lds + (bufoff) + ldsw + _i * 8192), 16, 0, 0); } while (0)
; #define PG8_LDA(dst, b, h) do { _Pragma("unroll") for (int m = 0; m < 4; ++m) _Pragma("unroll") for (int k = 0; k < 2; ++k) dst[m][k] = *(const LAS bf16x8*)(lds + PG8_SA(b, h) + aoff + m * 2048 + k * 1024); } while (0)
; #define PG8_LDB(dst, b, h) do { _Pragma("unroll") for (int n = 0; n < 2; ++n) _Pragma("unroll") for (int k = 0; k < 2; ++k) dst[n][k] = *(const LAS bf16x8*)(lds + PG8_SB(b, h) + boff + n * 2048 + k * 1024); } while (0)
; #define PG8_WAIT_V(n) asm volatile("s_waitcnt vmcnt(" #n ")" ::: "memory")
; #define PG8_WAIT_L(n) asm volatile("s_waitcnt lgkmcnt(" #n ")" ::: "memory")
; #define PG8_BAR __builtin_amdgcn_s_barrier()
; #define PG8_SCHED __builtin_amdgcn_sched_barrier(0)
; template <class Epi, class Sched, bool I8 = false>
; __device__ __forceinline__ void gemm_phase(LAS unsigned char* lds, const Gemm g, const Sched& S, const Epi& E) {
;     ...
;             const char* a1 = cA + (size_t)(t + 1) * kstep;
;             const char* a2 = last ? nA : cA + (size_t)(t + 2) * kstep; const char* b2 = last ? nB : cB + (size_t)(t + 2) * kstep;
;             const char* a3 = a2 + kstep; const char* b3 = b2 + kstep;
;             PG8_LDB(B0, 0, 0); PG8_LDB(B1, 0, 1); PG8_SCHED; PG8_LDA(At, 0, 0); PG8_STAGE(PG8_SA(1, 1), a1 + hstepA, voffA);
;             PG8_WAIT_V(8); PG8_WAIT_L(0); PG8_BAR; PG8_MMA(0, 0, At, B0); PG8_MMA(0, 1, At, B1); PG8_BAR; PG8_SCHED;
;             PG8_LDA(At, 0, 1); PG8_STAGE(PG8_SB(0, 0), b2, voffB); PG8_STAGE(PG8_SB(0, 1), b2 + hstepB, voffB); PG8_STAGE(PG8_SA(0, 0), a2, voffA);
;             PG8_WAIT_V(8); PG8_WAIT_L(0); PG8_BAR; PG8_MMA(1, 0, At, B0); PG8_MMA(1, 1, At, B1); PG8_BAR; PG8_SCHED;
.LBB0_1169:
	ds_read_b128 v[90:93], v169
	ds_read_b128 v[98:101], v169 offset:1024
	ds_read_b128 v[172:175], v169 offset:2048
	ds_read_b128 v[176:179], v169 offset:3072
	ds_read_b128 v[180:183], v170
	ds_read_b128 v[184:187], v170 offset:1024
	ds_read_b128 v[188:191], v170 offset:2048
	ds_read_b128 v[192:195], v170 offset:3072
	s_add_u32 s22, s20, 0x4000
	s_addc_u32 s23, s21, 0
	s_cmp_eq_u32 s53, 28
	s_cselect_b32 s26, s49, s22
	s_cselect_b32 s27, s13, s23
	s_cselect_b32 s24, s50, s51
	s_cselect_b32 s25, s11, s52
	s_add_u32 s22, s26, 0x8000
	s_addc_u32 s23, s27, 0
	s_sub_u32 s98, s20, 0x4000
	s_subb_u32 s99, s21, 0
	v_lshl_add_u64 v[158:159], s[98:99], 0, v[140:141]
	s_mov_b32 m0, s44
	s_nop 0
	global_load_lds_dwordx4 v[158:159], off
	v_lshl_add_u64 v[158:159], s[20:21], 0, v[148:149]
	s_add_i32 m0, s36, 0xc000
	ds_read_b128 v[196:199], v171
	ds_read_b128 v[200:203], v171 offset:1024
	ds_read_b128 v[204:207], v171 offset:2048
	ds_read_b128 v[208:211], v171 offset:3072
	ds_read_b128 v[212:215], v171 offset:4096
	ds_read_b128 v[216:219], v171 offset:5120
	ds_read_b128 v[220:223], v171 offset:6144
	ds_read_b128 v[224:227], v171 offset:7168
	global_load_lds_dwordx4 v[158:159], off
	v_lshl_add_u64 v[158:159], s[20:21], 0, v[150:151]
	s_add_i32 m0, s36, 0xe000
	s_nop 0
	global_load_lds_dwordx4 v[158:159], off
	s_waitcnt vmcnt(8)
	s_waitcnt lgkmcnt(0)
	s_barrier
	s_setprio 1
	s_waitcnt lgkmcnt(0)
	v_mfma_i32_16x16x64_i8 v[134:137], v[90:93], v[196:199], v[134:137]
	v_mfma_i32_16x16x64_i8 v[130:133], v[172:175], v[196:199], v[130:133]
	v_mfma_i32_16x16x64_i8 v[118:121], v[90:93], v[204:207], v[118:121]
	v_mfma_i32_16x16x64_i8 v[114:117], v[172:175], v[204:207], v[114:117]
	v_mfma_i32_16x16x64_i8 v[102:105], v[90:93], v[212:215], v[102:105]
	v_mfma_i32_16x16x64_i8 v[94:97], v[172:175], v[212:215], v[94:97]
	v_mfma_i32_16x16x64_i8 v[78:81], v[90:93], v[220:223], v[78:81]
	v_mfma_i32_16x16x64_i8 v[74:77], v[172:175], v[220:223], v[74:77]
	v_mfma_i32_16x16x64_i8 v[134:137], v[98:101], v[200:203], v[134:137]
	v_mfma_i32_16x16x64_i8 v[130:133], v[176:179], v[200:203], v[130:133]
	v_mfma_i32_16x16x64_i8 v[118:121], v[98:101], v[208:211], v[118:121]
	v_mfma_i32_16x16x64_i8 v[114:117], v[176:179], v[208:211], v[114:117]
	v_mfma_i32_16x16x64_i8 v[102:105], v[98:101], v[216:219], v[102:105]
	v_mfma_i32_16x16x64_i8 v[94:97], v[176:179], v[216:219], v[94:97]
	v_mfma_i32_16x16x64_i8 v[78:81], v[98:101], v[224:227], v[78:81]
	v_mfma_i32_16x16x64_i8 v[74:77], v[176:179], v[224:227], v[74:77]
	s_setprio 0
	s_setprio 1
	v_mfma_i32_16x16x64_i8 v[126:129], v[180:183], v[196:199], v[126:129]
	v_mfma_i32_16x16x64_i8 v[122:125], v[188:191], v[196:199], v[122:125]
	v_mfma_i32_16x16x64_i8 v[110:113], v[180:183], v[204:207], v[110:113]
	v_mfma_i32_16x16x64_i8 v[106:109], v[188:191], v[204:207], v[106:109]
	v_mfma_i32_16x16x64_i8 v[86:89], v[180:183], v[212:215], v[86:89]
	v_mfma_i32_16x16x64_i8 v[82:85], v[188:191], v[212:215], v[82:85]
	v_mfma_i32_16x16x64_i8 v[70:73], v[180:183], v[220:223], v[70:73]
	v_mfma_i32_16x16x64_i8 v[66:69], v[188:191], v[220:223], v[66:69]
	v_mfma_i32_16x16x64_i8 v[126:129], v[184:187], v[200:203], v[126:129]
	v_mfma_i32_16x16x64_i8 v[122:125], v[192:195], v[200:203], v[122:125]
	v_mfma_i32_16x16x64_i8 v[110:113], v[184:187], v[208:211], v[110:113]
	v_mfma_i32_16x16x64_i8 v[106:109], v[192:195], v[208:211], v[106:109]
	v_mfma_i32_16x16x64_i8 v[86:89], v[184:187], v[216:219], v[86:89]
	v_mfma_i32_16x16x64_i8 v[82:85], v[192:195], v[216:219], v[82:85]
	v_mfma_i32_16x16x64_i8 v[70:73], v[184:187], v[224:227], v[70:73]
	v_mfma_i32_16x16x64_i8 v[66:69], v[192:195], v[224:227], v[66:69]
	s_setprio 0
	s_barrier
	s_add_i32 s54, s46, s33
	v_lshl_add_u64 v[158:159], s[24:25], 0, v[142:143]
	s_mov_b32 m0, s54
	ds_read_b128 v[196:199], v171 offset:16384
	ds_read_b128 v[200:203], v171 offset:17408
	ds_read_b128 v[204:207], v171 offset:18432
	ds_read_b128 v[208:211], v171 offset:19456
	ds_read_b128 v[212:215], v171 offset:20480
	ds_read_b128 v[216:219], v171 offset:21504
	ds_read_b128 v[220:223], v171 offset:22528
	ds_read_b128 v[224:227], v171 offset:23552
	global_load_lds_dwordx4 v[158:159], off
	s_add_i32 m0, s54, 0x2000
	s_add_u32 s54, s24, 0x4000
	v_lshl_add_u64 v[158:159], s[24:25], 0, v[138:139]
	s_addc_u32 s55, s25, 0
	s_add_i32 s56, s47, s33
	global_load_lds_dwordx4 v[158:159], off
	v_lshl_add_u64 v[158:159], s[54:55], 0, v[142:143]
	s_mov_b32 m0, s56
	s_nop 0
	global_load_lds_dwordx4 v[158:159], off
	v_lshl_add_u64 v[158:159], s[54:55], 0, v[138:139]
	s_add_i32 m0, s56, 0x2000
	s_nop 0
	global_load_lds_dwordx4 v[158:159], off
	v_lshl_add_u64 v[158:159], s[26:27], 0, v[144:145]
	s_mov_b32 m0, s36
	s_nop 0
	global_load_lds_dwordx4 v[158:159], off
	s_waitcnt vmcnt(7)
	s_waitcnt lgkmcnt(0)
	s_barrier
; #define PG8_STAGE(bufoff, gbase, voff) do { _Pragma("unroll") for (int _i = 0; _i < 2; ++_i) \
;         __builtin_amdgcn_global_load_lds((const unsigned*)((const char*)(gbase) + (voff)[_i]), (LAS unsigned*)(lds + (bufoff) + ldsw + _i * 8192), 16, 0, 0); } while (0)
; #define PG8_LDA(dst, b, h) do { _Pragma("unroll") for (int m = 0; m < 4; ++m) _Pragma("unroll") for (int k = 0; k < 2; ++k) dst[m][k] = *(const LAS bf16x8*)(lds + PG8_SA(b, h) + aoff + m * 2048 + k * 1024); } while (0)
; #define PG8_LDB(dst, b, h) do { _Pragma("unroll") for (int n = 0; n < 2; ++n) _Pragma("unroll") for (int k = 0; k < 2; ++k) dst[n][k] = *(const LAS bf16x8*)(lds + PG8_SB(b, h) + boff + n * 2048 + k * 1024); } while (0)
; #define PG8_WAIT_V(n) asm volatile("s_waitcnt vmcnt(" #n ")" ::: "memory")
; #define PG8_WAIT_L(n) asm volatile("s_waitcnt lgkmcnt(" #n ")" ::: "memory")
; #define PG8_BAR __builtin_amdgcn_s_barrier()
; #define PG8_SCHED __builtin_amdgcn_sched_barrier(0)
; template <class Epi, class Sched, bool I8 = false>
; __device__ __forceinline__ void gemm_phase(LAS unsigned char* lds, const Gemm g, const Sched& S, const Epi& E) {
;     ...
;             PG8_WAIT_V(8); PG8_WAIT_L(0); PG8_BAR; PG8_MMA(1, 0, At, B0); PG8_MMA(1, 1, At, B1); PG8_BAR; PG8_SCHED;
;             PG8_LDB(B0, 1, 0); PG8_LDB(B1, 1, 1); PG8_SCHED; PG8_LDA(At, 1, 0); PG8_STAGE(PG8_SA(0, 1), a2 + hstepA, voffA);
;             PG8_WAIT_V(8); PG8_WAIT_L(0); PG8_BAR; PG8_MMA(0, 0, At, B0); PG8_MMA(0, 1, At, B1); PG8_BAR; PG8_SCHED;
	s_setprio 1
	s_waitcnt lgkmcnt(0)
	v_mfma_i32_16x16x64_i8 v[62:65], v[90:93], v[196:199], v[62:65]
	v_mfma_i32_16x16x64_i8 v[58:61], v[172:175], v[196:199], v[58:61]
	v_mfma_i32_16x16x64_i8 v[46:49], v[90:93], v[204:207], v[46:49]
	v_mfma_i32_16x16x64_i8 v[42:45], v[172:175], v[204:207], v[42:45]
	v_mfma_i32_16x16x64_i8 v[30:33], v[90:93], v[212:215], v[30:33]
	v_mfma_i32_16x16x64_i8 v[26:29], v[172:175], v[212:215], v[26:29]
	v_mfma_i32_16x16x64_i8 v[14:17], v[90:93], v[220:223], v[14:17]
	v_mfma_i32_16x16x64_i8 v[10:13], v[172:175], v[220:223], v[10:13]
	v_mfma_i32_16x16x64_i8 v[62:65], v[98:101], v[200:203], v[62:65]
	v_mfma_i32_16x16x64_i8 v[58:61], v[176:179], v[200:203], v[58:61]
	v_mfma_i32_16x16x64_i8 v[46:49], v[98:101], v[208:211], v[46:49]
	v_mfma_i32_16x16x64_i8 v[42:45], v[176:179], v[208:211], v[42:45]
	v_mfma_i32_16x16x64_i8 v[30:33], v[98:101], v[216:219], v[30:33]
	v_mfma_i32_16x16x64_i8 v[26:29], v[176:179], v[216:219], v[26:29]
	v_mfma_i32_16x16x64_i8 v[14:17], v[98:101], v[224:227], v[14:17]
	v_mfma_i32_16x16x64_i8 v[10:13], v[176:179], v[224:227], v[10:13]
	s_setprio 0
	s_setprio 1
	v_mfma_i32_16x16x64_i8 v[54:57], v[180:183], v[196:199], v[54:57]
	v_mfma_i32_16x16x64_i8 v[50:53], v[188:191], v[196:199], v[50:53]
	v_mfma_i32_16x16x64_i8 v[38:41], v[180:183], v[204:207], v[38:41]
	v_mfma_i32_16x16x64_i8 v[34:37], v[188:191], v[204:207], v[34:37]
	v_mfma_i32_16x16x64_i8 v[22:25], v[180:183], v[212:215], v[22:25]
	v_mfma_i32_16x16x64_i8 v[18:21], v[188:191], v[212:215], v[18:21]
	v_mfma_i32_16x16x64_i8 v[6:9], v[180:183], v[220:223], v[6:9]
	v_mfma_i32_16x16x64_i8 v[2:5], v[188:191], v[220:223], v[2:5]
	v_mfma_i32_16x16x64_i8 v[54:57], v[184:187], v[200:203], v[54:57]
	v_mfma_i32_16x16x64_i8 v[50:53], v[192:195], v[200:203], v[50:53]
	v_mfma_i32_16x16x64_i8 v[38:41], v[184:187], v[208:211], v[38:41]
	v_mfma_i32_16x16x64_i8 v[34:37], v[192:195], v[208:211], v[34:37]
	v_mfma_i32_16x16x64_i8 v[22:25], v[184:187], v[216:219], v[22:25]
	v_mfma_i32_16x16x64_i8 v[18:21], v[192:195], v[216:219], v[18:21]
	v_mfma_i32_16x16x64_i8 v[6:9], v[184:187], v[224:227], v[6:9]
	v_mfma_i32_16x16x64_i8 v[2:5], v[192:195], v[224:227], v[2:5]
	s_setprio 0
	s_barrier
	s_add_i32 s54, 0, 0x18000
	v_add_u32_e32 v146, s54, v165
	s_add_i32 s55, 0, 0x1c000
	ds_read_b128 v[90:93], v146
	ds_read_b128 v[98:101], v146 offset:1024
	ds_read_b128 v[172:175], v146 offset:2048
	ds_read_b128 v[176:179], v146 offset:3072
	v_add_u32_e32 v146, s55, v165
	ds_read_b128 v[180:183], v146
	ds_read_b128 v[184:187], v146 offset:1024
	ds_read_b128 v[188:191], v146 offset:2048
	ds_read_b128 v[192:195], v146 offset:3072
	v_lshl_add_u64 v[158:159], s[26:27], 0, v[140:141]
	s_mov_b32 m0, s37
	s_nop 0
	global_load_lds_dwordx4 v[158:159], off
	s_add_u32 s26, s26, 0x4000
	s_addc_u32 s27, s27, 0
	s_mov_b32 m0, s38
	v_lshl_add_u64 v[158:159], s[26:27], 0, v[144:145]
	ds_read_b128 v[196:199], v171 offset:32768
	ds_read_b128 v[200:203], v171 offset:33792
	ds_read_b128 v[204:207], v171 offset:34816
	ds_read_b128 v[208:211], v171 offset:35840
	ds_read_b128 v[212:215], v171 offset:36864
	ds_read_b128 v[216:219], v171 offset:37888
	ds_read_b128 v[220:223], v171 offset:38912
	ds_read_b128 v[224:227], v171 offset:39936
	global_load_lds_dwordx4 v[158:159], off
	v_lshl_add_u64 v[158:159], s[26:27], 0, v[140:141]
	s_mov_b32 m0, s39
	s_nop 0
	global_load_lds_dwordx4 v[158:159], off
	s_waitcnt vmcnt(8)
	s_waitcnt lgkmcnt(0)
	s_barrier
	s_setprio 1
	s_waitcnt lgkmcnt(0)
	v_mfma_i32_16x16x64_i8 v[134:137], v[90:93], v[196:199], v[134:137]
	v_mfma_i32_16x16x64_i8 v[130:133], v[172:175], v[196:199], v[130:133]
	v_mfma_i32_16x16x64_i8 v[118:121], v[90:93], v[204:207], v[118:121]
	v_mfma_i32_16x16x64_i8 v[114:117], v[172:175], v[204:207], v[114:117]
	v_mfma_i32_16x16x64_i8 v[102:105], v[90:93], v[212:215], v[102:105]
	v_mfma_i32_16x16x64_i8 v[94:97], v[172:175], v[212:215], v[94:97]
	v_mfma_i32_16x16x64_i8 v[78:81], v[90:93], v[220:223], v[78:81]
	v_mfma_i32_16x16x64_i8 v[74:77], v[172:175], v[220:223], v[74:77]
	v_mfma_i32_16x16x64_i8 v[134:137], v[98:101], v[200:203], v[134:137]
	v_mfma_i32_16x16x64_i8 v[130:133], v[176:179], v[200:203], v[130:133]
	v_mfma_i32_16x16x64_i8 v[118:121], v[98:101], v[208:211], v[118:121]
	v_mfma_i32_16x16x64_i8 v[114:117], v[176:179], v[208:211], v[114:117]
	v_mfma_i32_16x16x64_i8 v[102:105], v[98:101], v[216:219], v[102:105]
	v_mfma_i32_16x16x64_i8 v[94:97], v[176:179], v[216:219], v[94:97]
	v_mfma_i32_16x16x64_i8 v[78:81], v[98:101], v[224:227], v[78:81]
	v_mfma_i32_16x16x64_i8 v[74:77], v[176:179], v[224:227], v[74:77]
	s_setprio 0
	s_setprio 1
	v_mfma_i32_16x16x64_i8 v[126:129], v[180:183], v[196:199], v[126:129]
	v_mfma_i32_16x16x64_i8 v[122:125], v[188:191], v[196:199], v[122:125]
	v_mfma_i32_16x16x64_i8 v[110:113], v[180:183], v[204:207], v[110:113]
	v_mfma_i32_16x16x64_i8 v[106:109], v[188:191], v[204:207], v[106:109]
	v_mfma_i32_16x16x64_i8 v[86:89], v[180:183], v[212:215], v[86:89]
	v_mfma_i32_16x16x64_i8 v[82:85], v[188:191], v[212:215], v[82:85]
	v_mfma_i32_16x16x64_i8 v[70:73], v[180:183], v[220:223], v[70:73]
	v_mfma_i32_16x16x64_i8 v[66:69], v[188:191], v[220:223], v[66:69]
	v_mfma_i32_16x16x64_i8 v[126:129], v[184:187], v[200:203], v[126:129]
	v_mfma_i32_16x16x64_i8 v[122:125], v[192:195], v[200:203], v[122:125]
	v_mfma_i32_16x16x64_i8 v[110:113], v[184:187], v[208:211], v[110:113]
	v_mfma_i32_16x16x64_i8 v[106:109], v[192:195], v[208:211], v[106:109]
	v_mfma_i32_16x16x64_i8 v[86:89], v[184:187], v[216:219], v[86:89]
	v_mfma_i32_16x16x64_i8 v[82:85], v[192:195], v[216:219], v[82:85]
	v_mfma_i32_16x16x64_i8 v[70:73], v[184:187], v[224:227], v[70:73]
	v_mfma_i32_16x16x64_i8 v[66:69], v[192:195], v[224:227], v[66:69]
	s_setprio 0
	s_barrier
; #define PG8_STAGE(bufoff, gbase, voff) do { _Pragma("unroll") for (int _i = 0; _i < 2; ++_i) \
;         __builtin_amdgcn_global_load_lds((const unsigned*)((const char*)(gbase) + (voff)[_i]), (LAS unsigned*)(lds + (bufoff) + ldsw + _i * 8192), 16, 0, 0); } while (0)
; #define PG8_LDA(dst, b, h) do { _Pragma("unroll") for (int m = 0; m < 4; ++m) _Pragma("unroll") for (int k = 0; k < 2; ++k) dst[m][k] = *(const LAS bf16x8*)(lds + PG8_SA(b, h) + aoff + m * 2048 + k * 1024); } while (0)
; #define PG8_WAIT_V(n) asm volatile("s_waitcnt vmcnt(" #n ")" ::: "memory")
; #define PG8_WAIT_L(n) asm volatile("s_waitcnt lgkmcnt(" #n ")" ::: "memory")
; #define PG8_BAR __builtin_amdgcn_s_barrier()
; #define PG8_SCHED __builtin_amdgcn_sched_barrier(0)
; template <class Epi, class Sched, bool I8 = false>
; __device__ __forceinline__ void gemm_phase(LAS unsigned char* lds, const Gemm g, const Sched& S, const Epi& E) {
;     ...
;             PG8_LDA(At, 1, 1); PG8_STAGE(PG8_SB(1, 0), b3, voffB); PG8_STAGE(PG8_SB(1, 1), b3 + hstepB, voffB); PG8_STAGE(PG8_SA(1, 0), a3, voffA);
;             PG8_WAIT_V(8); PG8_WAIT_L(0); PG8_BAR; PG8_MMA(1, 0, At, B0); PG8_MMA(1, 1, At, B1); PG8_BAR; PG8_SCHED;
;         }
;         if (wr == 0) PG8_BAR;
	s_add_u32 s26, s24, 0x8000
	s_addc_u32 s27, s25, 0
	s_add_i32 s54, s54, s33
	v_lshl_add_u64 v[158:159], s[26:27], 0, v[142:143]
	s_mov_b32 m0, s54
	ds_read_b128 v[196:199], v171 offset:49152
	ds_read_b128 v[200:203], v171 offset:50176
	ds_read_b128 v[204:207], v171 offset:51200
	ds_read_b128 v[208:211], v171 offset:52224
	ds_read_b128 v[212:215], v171 offset:53248
	ds_read_b128 v[216:219], v171 offset:54272
	ds_read_b128 v[220:223], v171 offset:55296
	ds_read_b128 v[224:227], v171 offset:56320
	global_load_lds_dwordx4 v[158:159], off
	s_add_i32 m0, s54, 0x2000
	s_add_u32 s24, s24, 0xc000
	v_lshl_add_u64 v[158:159], s[26:27], 0, v[138:139]
	s_addc_u32 s25, s25, 0
	s_add_i32 s26, s55, s33
	global_load_lds_dwordx4 v[158:159], off
	v_lshl_add_u64 v[158:159], s[24:25], 0, v[142:143]
	s_mov_b32 m0, s26
	s_nop 0
	global_load_lds_dwordx4 v[158:159], off
	v_lshl_add_u64 v[158:159], s[24:25], 0, v[138:139]
	s_add_i32 m0, s26, 0x2000
	s_nop 0
	global_load_lds_dwordx4 v[158:159], off
	v_lshl_add_u64 v[158:159], s[22:23], 0, v[144:145]
	s_mov_b32 m0, s43
	s_nop 0
	global_load_lds_dwordx4 v[158:159], off
	s_waitcnt vmcnt(7)
	s_waitcnt lgkmcnt(0)
	s_barrier
	s_setprio 1
	s_waitcnt lgkmcnt(0)
	v_mfma_i32_16x16x64_i8 v[62:65], v[90:93], v[196:199], v[62:65]
	v_mfma_i32_16x16x64_i8 v[58:61], v[172:175], v[196:199], v[58:61]
	v_mfma_i32_16x16x64_i8 v[46:49], v[90:93], v[204:207], v[46:49]
	v_mfma_i32_16x16x64_i8 v[42:45], v[172:175], v[204:207], v[42:45]
	v_mfma_i32_16x16x64_i8 v[30:33], v[90:93], v[212:215], v[30:33]
	v_mfma_i32_16x16x64_i8 v[26:29], v[172:175], v[212:215], v[26:29]
	v_mfma_i32_16x16x64_i8 v[14:17], v[90:93], v[220:223], v[14:17]
	v_mfma_i32_16x16x64_i8 v[10:13], v[172:175], v[220:223], v[10:13]
	v_mfma_i32_16x16x64_i8 v[62:65], v[98:101], v[200:203], v[62:65]
	v_mfma_i32_16x16x64_i8 v[58:61], v[176:179], v[200:203], v[58:61]
	v_mfma_i32_16x16x64_i8 v[46:49], v[98:101], v[208:211], v[46:49]
	v_mfma_i32_16x16x64_i8 v[42:45], v[176:179], v[208:211], v[42:45]
	v_mfma_i32_16x16x64_i8 v[30:33], v[98:101], v[216:219], v[30:33]
	v_mfma_i32_16x16x64_i8 v[26:29], v[176:179], v[216:219], v[26:29]
	v_mfma_i32_16x16x64_i8 v[14:17], v[98:101], v[224:227], v[14:17]
	v_mfma_i32_16x16x64_i8 v[10:13], v[176:179], v[224:227], v[10:13]
	s_setprio 0
	s_setprio 1
	v_mfma_i32_16x16x64_i8 v[54:57], v[180:183], v[196:199], v[54:57]
	v_mfma_i32_16x16x64_i8 v[50:53], v[188:191], v[196:199], v[50:53]
	v_mfma_i32_16x16x64_i8 v[38:41], v[180:183], v[204:207], v[38:41]
	v_mfma_i32_16x16x64_i8 v[34:37], v[188:191], v[204:207], v[34:37]
	v_mfma_i32_16x16x64_i8 v[22:25], v[180:183], v[212:215], v[22:25]
	v_mfma_i32_16x16x64_i8 v[18:21], v[188:191], v[212:215], v[18:21]
	v_mfma_i32_16x16x64_i8 v[6:9], v[180:183], v[220:223], v[6:9]
	v_mfma_i32_16x16x64_i8 v[2:5], v[188:191], v[220:223], v[2:5]
	v_mfma_i32_16x16x64_i8 v[54:57], v[184:187], v[200:203], v[54:57]
	v_mfma_i32_16x16x64_i8 v[50:53], v[192:195], v[200:203], v[50:53]
	v_mfma_i32_16x16x64_i8 v[38:41], v[184:187], v[208:211], v[38:41]
	v_mfma_i32_16x16x64_i8 v[34:37], v[192:195], v[208:211], v[34:37]
	v_mfma_i32_16x16x64_i8 v[22:25], v[184:187], v[216:219], v[22:25]
	v_mfma_i32_16x16x64_i8 v[18:21], v[192:195], v[216:219], v[18:21]
	v_mfma_i32_16x16x64_i8 v[6:9], v[184:187], v[224:227], v[6:9]
	v_mfma_i32_16x16x64_i8 v[2:5], v[192:195], v[224:227], v[2:5]
	s_setprio 0
	s_barrier
	s_add_i32 s53, s53, 2
	s_add_u32 s20, s20, 0x10000
	s_addc_u32 s21, s21, 0
	s_add_u32 s51, s51, 0x10000
	s_addc_u32 s52, s52, 0
	s_cmp_gt_u32 s53, 29
	s_cbranch_scc0 .LBB0_1169
	s_and_b64 vcc, exec, s[8:9]
	s_cbranch_vccz .LBB0_1172
	s_barrier

; #define PG8_STAGE(bufoff, gbase, voff) do { _Pragma("unroll") for (int _i = 0; _i < 2; ++_i) \
;         __builtin_amdgcn_global_load_lds((const unsigned*)((const char*)(gbase) + (voff)[_i]), (LAS unsigned*)(lds + (bufoff) + ldsw + _i * 8192), 16, 0, 0); } while (0)
; #define PG8_LDA(dst, b, h) do { _Pragma("unroll") for (int m = 0; m < 4; ++m) _Pragma("unroll") for (int k = 0; k < 2; ++k) dst[m][k] = *(const LAS bf16x8*)(lds + PG8_SA(b, h) + aoff + m * 2048 + k * 1024); } while (0)
; #define PG8_LDB(dst, b, h) do { _Pragma("unroll") for (int n = 0; n < 2; ++n) _Pragma("unroll") for (int k = 0; k < 2; ++k) dst[n][k] = *(const LAS bf16x8*)(lds + PG8_SB(b, h) + boff + n * 2048 + k * 1024); } while (0)
; #define PG8_WAIT_V(n) asm volatile("s_waitcnt vmcnt(" #n ")" ::: "memory")
; #define PG8_WAIT_L(n) asm volatile("s_waitcnt lgkmcnt(" #n ")" ::: "memory")
; #define PG8_BAR __builtin_amdgcn_s_barrier()
; #define PG8_SCHED __builtin_amdgcn_sched_barrier(0)
; template <class Epi, class Sched, bool I8 = false>
; __device__ __forceinline__ void gemm_phase(LAS unsigned char* lds, const Gemm g, const Sched& S, const Epi& E) {
;     ...
;             const char* a1 = cA + (size_t)(t + 1) * kstep;
;             const char* a2 = last ? nA : cA + (size_t)(t + 2) * kstep; const char* b2 = last ? nB : cB + (size_t)(t + 2) * kstep;
;             const char* a3 = a2 + kstep; const char* b3 = b2 + kstep;
;             PG8_LDB(B0, 0, 0); PG8_LDB(B1, 0, 1); PG8_SCHED; PG8_LDA(At, 0, 0); PG8_STAGE(PG8_SA(1, 1), a1 + hstepA, voffA);
;             PG8_WAIT_V(8); PG8_WAIT_L(0); PG8_BAR; PG8_MMA(0, 0, At, B0); PG8_MMA(0, 1, At, B1); PG8_BAR; PG8_SCHED;
;             PG8_LDA(At, 0, 1); PG8_STAGE(PG8_SB(0, 0), b2, voffB); PG8_STAGE(PG8_SB(0, 1), b2 + hstepB, voffB); PG8_STAGE(PG8_SA(0, 0), a2, voffA);
;             PG8_WAIT_V(8); PG8_WAIT_L(0); PG8_BAR; PG8_MMA(1, 0, At, B0); PG8_MMA(1, 1, At, B1); PG8_BAR; PG8_SCHED;
.LBB0_1393:
	ds_read_b128 v[66:69], v180
	ds_read_b128 v[70:73], v180 offset:1024
	ds_read_b128 v[74:77], v180 offset:2048
	ds_read_b128 v[78:81], v180 offset:3072
	ds_read_b128 v[146:149], v181
	ds_read_b128 v[150:153], v181 offset:1024
	ds_read_b128 v[174:177], v181 offset:2048
	ds_read_b128 v[184:187], v181 offset:3072
	s_add_u32 s20, s18, 0x4000
	s_addc_u32 s21, s19, 0
	s_cmpk_eq_i32 s49, 0x52
	s_cselect_b32 s24, s0, s20
	s_cselect_b32 s25, s1, s21
	s_cselect_b32 s22, s16, s47
	s_cselect_b32 s23, s17, s48
	s_add_u32 s20, s24, 0x8000
	s_addc_u32 s21, s25, 0
	s_sub_u32 s98, s18, 0x4000
	s_subb_u32 s99, s19, 0
	v_lshl_add_u64 v[220:221], s[98:99], 0, v[160:161]
	s_mov_b32 m0, s38
	s_nop 0
	global_load_lds_dwordx4 v[220:221], off
	v_lshl_add_u64 v[220:221], s[18:19], 0, v[166:167]
	s_add_i32 m0, s31, 0xc000
	ds_read_b128 v[188:191], v182
	ds_read_b128 v[192:195], v182 offset:1024
	ds_read_b128 v[196:199], v182 offset:2048
	ds_read_b128 v[200:203], v182 offset:3072
	ds_read_b128 v[204:207], v182 offset:4096
	ds_read_b128 v[208:211], v182 offset:5120
	ds_read_b128 v[212:215], v182 offset:6144
	ds_read_b128 v[216:219], v182 offset:7168
	global_load_lds_dwordx4 v[220:221], off
	v_lshl_add_u64 v[220:221], s[18:19], 0, v[168:169]
	s_add_i32 m0, s31, 0xe000
	s_nop 0
	global_load_lds_dwordx4 v[220:221], off
	s_waitcnt vmcnt(8)
	s_waitcnt lgkmcnt(0)
	s_barrier
	s_setprio 1
	s_waitcnt lgkmcnt(0)
	v_mfma_i32_16x16x64_i8 v[142:145], v[66:69], v[188:191], v[142:145]
	v_mfma_i32_16x16x64_i8 v[138:141], v[74:77], v[188:191], v[138:141]
	v_mfma_i32_16x16x64_i8 v[126:129], v[66:69], v[196:199], v[126:129]
	v_mfma_i32_16x16x64_i8 v[122:125], v[74:77], v[196:199], v[122:125]
	v_mfma_i32_16x16x64_i8 v[110:113], v[66:69], v[204:207], v[110:113]
	v_mfma_i32_16x16x64_i8 v[106:109], v[74:77], v[204:207], v[106:109]
	v_mfma_i32_16x16x64_i8 v[94:97], v[66:69], v[212:215], v[94:97]
	v_mfma_i32_16x16x64_i8 v[90:93], v[74:77], v[212:215], v[90:93]
	v_mfma_i32_16x16x64_i8 v[142:145], v[70:73], v[192:195], v[142:145]
	v_mfma_i32_16x16x64_i8 v[138:141], v[78:81], v[192:195], v[138:141]
	v_mfma_i32_16x16x64_i8 v[126:129], v[70:73], v[200:203], v[126:129]
	v_mfma_i32_16x16x64_i8 v[122:125], v[78:81], v[200:203], v[122:125]
	v_mfma_i32_16x16x64_i8 v[110:113], v[70:73], v[208:211], v[110:113]
	v_mfma_i32_16x16x64_i8 v[106:109], v[78:81], v[208:211], v[106:109]
	v_mfma_i32_16x16x64_i8 v[94:97], v[70:73], v[216:219], v[94:97]
	v_mfma_i32_16x16x64_i8 v[90:93], v[78:81], v[216:219], v[90:93]
	s_setprio 0
	s_setprio 1
	v_mfma_i32_16x16x64_i8 v[134:137], v[146:149], v[188:191], v[134:137]
	v_mfma_i32_16x16x64_i8 v[130:133], v[174:177], v[188:191], v[130:133]
	v_mfma_i32_16x16x64_i8 v[118:121], v[146:149], v[196:199], v[118:121]
	v_mfma_i32_16x16x64_i8 v[114:117], v[174:177], v[196:199], v[114:117]
	v_mfma_i32_16x16x64_i8 v[102:105], v[146:149], v[204:207], v[102:105]
	v_mfma_i32_16x16x64_i8 v[98:101], v[174:177], v[204:207], v[98:101]
	v_mfma_i32_16x16x64_i8 v[86:89], v[146:149], v[212:215], v[86:89]
	v_mfma_i32_16x16x64_i8 v[82:85], v[174:177], v[212:215], v[82:85]
	v_mfma_i32_16x16x64_i8 v[134:137], v[150:153], v[192:195], v[134:137]
	v_mfma_i32_16x16x64_i8 v[130:133], v[184:187], v[192:195], v[130:133]
	v_mfma_i32_16x16x64_i8 v[118:121], v[150:153], v[200:203], v[118:121]
	v_mfma_i32_16x16x64_i8 v[114:117], v[184:187], v[200:203], v[114:117]
	v_mfma_i32_16x16x64_i8 v[102:105], v[150:153], v[208:211], v[102:105]
	v_mfma_i32_16x16x64_i8 v[98:101], v[184:187], v[208:211], v[98:101]
	v_mfma_i32_16x16x64_i8 v[86:89], v[150:153], v[216:219], v[86:89]
	v_mfma_i32_16x16x64_i8 v[82:85], v[184:187], v[216:219], v[82:85]
	s_setprio 0
	s_barrier
	s_add_i32 s50, s41, s30
	v_lshl_add_u64 v[220:221], s[22:23], 0, v[158:159]
	s_mov_b32 m0, s50
	ds_read_b128 v[188:191], v182 offset:16384
	ds_read_b128 v[192:195], v182 offset:17408
	ds_read_b128 v[196:199], v182 offset:18432
	ds_read_b128 v[200:203], v182 offset:19456
	ds_read_b128 v[204:207], v182 offset:20480
	ds_read_b128 v[208:211], v182 offset:21504
	ds_read_b128 v[212:215], v182 offset:22528
	ds_read_b128 v[216:219], v182 offset:23552
	global_load_lds_dwordx4 v[220:221], off
	s_add_i32 m0, s50, 0x2000
	s_add_u32 s50, s22, 0x4000
	v_lshl_add_u64 v[220:221], s[22:23], 0, v[162:163]
	s_addc_u32 s51, s23, 0
	s_add_i32 s52, s42, s30
	global_load_lds_dwordx4 v[220:221], off
	v_lshl_add_u64 v[220:221], s[50:51], 0, v[158:159]
	s_mov_b32 m0, s52
	s_nop 0
	global_load_lds_dwordx4 v[220:221], off
	v_lshl_add_u64 v[220:221], s[50:51], 0, v[162:163]
	s_add_i32 m0, s52, 0x2000
	s_nop 0
	global_load_lds_dwordx4 v[220:221], off
	v_lshl_add_u64 v[220:221], s[24:25], 0, v[156:157]
	s_mov_b32 m0, s31
	s_nop 0
	global_load_lds_dwordx4 v[220:221], off
	s_waitcnt vmcnt(7)
	s_waitcnt lgkmcnt(0)
	s_barrier
; #define PG8_STAGE(bufoff, gbase, voff) do { _Pragma("unroll") for (int _i = 0; _i < 2; ++_i) \
;         __builtin_amdgcn_global_load_lds((const unsigned*)((const char*)(gbase) + (voff)[_i]), (LAS unsigned*)(lds + (bufoff) + ldsw + _i * 8192), 16, 0, 0); } while (0)
; #define PG8_LDA(dst, b, h) do { _Pragma("unroll") for (int m = 0; m < 4; ++m) _Pragma("unroll") for (int k = 0; k < 2; ++k) dst[m][k] = *(const LAS bf16x8*)(lds + PG8_SA(b, h) + aoff + m * 2048 + k * 1024); } while (0)
; #define PG8_LDB(dst, b, h) do { _Pragma("unroll") for (int n = 0; n < 2; ++n) _Pragma("unroll") for (int k = 0; k < 2; ++k) dst[n][k] = *(const LAS bf16x8*)(lds + PG8_SB(b, h) + boff + n * 2048 + k * 1024); } while (0)
; #define PG8_WAIT_V(n) asm volatile("s_waitcnt vmcnt(" #n ")" ::: "memory")
; #define PG8_WAIT_L(n) asm volatile("s_waitcnt lgkmcnt(" #n ")" ::: "memory")
; #define PG8_BAR __builtin_amdgcn_s_barrier()
; #define PG8_SCHED __builtin_amdgcn_sched_barrier(0)
; template <class Epi, class Sched, bool I8 = false>
; __device__ __forceinline__ void gemm_phase(LAS unsigned char* lds, const Gemm g, const Sched& S, const Epi& E) {
;     ...
;             PG8_WAIT_V(8); PG8_WAIT_L(0); PG8_BAR; PG8_MMA(1, 0, At, B0); PG8_MMA(1, 1, At, B1); PG8_BAR; PG8_SCHED;
;             PG8_LDB(B0, 1, 0); PG8_LDB(B1, 1, 1); PG8_SCHED; PG8_LDA(At, 1, 0); PG8_STAGE(PG8_SA(0, 1), a2 + hstepA, voffA);
;             PG8_WAIT_V(8); PG8_WAIT_L(0); PG8_BAR; PG8_MMA(0, 0, At, B0); PG8_MMA(0, 1, At, B1); PG8_BAR; PG8_SCHED;
	s_setprio 1
	s_waitcnt lgkmcnt(0)
	v_mfma_i32_16x16x64_i8 v[62:65], v[66:69], v[188:191], v[62:65]
	v_mfma_i32_16x16x64_i8 v[58:61], v[74:77], v[188:191], v[58:61]
	v_mfma_i32_16x16x64_i8 v[46:49], v[66:69], v[196:199], v[46:49]
	v_mfma_i32_16x16x64_i8 v[42:45], v[74:77], v[196:199], v[42:45]
	v_mfma_i32_16x16x64_i8 v[30:33], v[66:69], v[204:207], v[30:33]
	v_mfma_i32_16x16x64_i8 v[26:29], v[74:77], v[204:207], v[26:29]
	v_mfma_i32_16x16x64_i8 v[14:17], v[66:69], v[212:215], v[14:17]
	v_mfma_i32_16x16x64_i8 v[10:13], v[74:77], v[212:215], v[10:13]
	v_mfma_i32_16x16x64_i8 v[62:65], v[70:73], v[192:195], v[62:65]
	v_mfma_i32_16x16x64_i8 v[58:61], v[78:81], v[192:195], v[58:61]
	v_mfma_i32_16x16x64_i8 v[46:49], v[70:73], v[200:203], v[46:49]
	v_mfma_i32_16x16x64_i8 v[42:45], v[78:81], v[200:203], v[42:45]
	v_mfma_i32_16x16x64_i8 v[30:33], v[70:73], v[208:211], v[30:33]
	v_mfma_i32_16x16x64_i8 v[26:29], v[78:81], v[208:211], v[26:29]
	v_mfma_i32_16x16x64_i8 v[14:17], v[70:73], v[216:219], v[14:17]
	v_mfma_i32_16x16x64_i8 v[10:13], v[78:81], v[216:219], v[10:13]
	s_setprio 0
	s_setprio 1
	v_mfma_i32_16x16x64_i8 v[54:57], v[146:149], v[188:191], v[54:57]
	v_mfma_i32_16x16x64_i8 v[50:53], v[174:177], v[188:191], v[50:53]
	v_mfma_i32_16x16x64_i8 v[38:41], v[146:149], v[196:199], v[38:41]
	v_mfma_i32_16x16x64_i8 v[34:37], v[174:177], v[196:199], v[34:37]
	v_mfma_i32_16x16x64_i8 v[22:25], v[146:149], v[204:207], v[22:25]
	v_mfma_i32_16x16x64_i8 v[18:21], v[174:177], v[204:207], v[18:21]
	v_mfma_i32_16x16x64_i8 v[6:9], v[146:149], v[212:215], v[6:9]
	v_mfma_i32_16x16x64_i8 v[2:5], v[174:177], v[212:215], v[2:5]
	v_mfma_i32_16x16x64_i8 v[54:57], v[150:153], v[192:195], v[54:57]
	v_mfma_i32_16x16x64_i8 v[50:53], v[184:187], v[192:195], v[50:53]
	v_mfma_i32_16x16x64_i8 v[38:41], v[150:153], v[200:203], v[38:41]
	v_mfma_i32_16x16x64_i8 v[34:37], v[184:187], v[200:203], v[34:37]
	v_mfma_i32_16x16x64_i8 v[22:25], v[150:153], v[208:211], v[22:25]
	v_mfma_i32_16x16x64_i8 v[18:21], v[184:187], v[208:211], v[18:21]
	v_mfma_i32_16x16x64_i8 v[6:9], v[150:153], v[216:219], v[6:9]
	v_mfma_i32_16x16x64_i8 v[2:5], v[184:187], v[216:219], v[2:5]
	s_setprio 0
	s_barrier
	s_add_i32 s50, 0, 0x18000
	s_add_i32 s51, 0, 0x1c000
	v_add_u32_e32 v78, s50, v178
	v_add_u32_e32 v164, s51, v178
	ds_read_b128 v[66:69], v78
	ds_read_b128 v[70:73], v78 offset:1024
	ds_read_b128 v[74:77], v78 offset:2048
	ds_read_b128 v[78:81], v78 offset:3072
	ds_read_b128 v[146:149], v164
	ds_read_b128 v[150:153], v164 offset:1024
	ds_read_b128 v[174:177], v164 offset:2048
	ds_read_b128 v[184:187], v164 offset:3072
	v_lshl_add_u64 v[220:221], s[24:25], 0, v[160:161]
	s_mov_b32 m0, s33
	s_nop 0
	global_load_lds_dwordx4 v[220:221], off
	s_add_u32 s24, s24, 0x4000
	s_addc_u32 s25, s25, 0
	s_mov_b32 m0, s34
	v_lshl_add_u64 v[220:221], s[24:25], 0, v[156:157]
	ds_read_b128 v[188:191], v182 offset:32768
	ds_read_b128 v[192:195], v182 offset:33792
	ds_read_b128 v[196:199], v182 offset:34816
	ds_read_b128 v[200:203], v182 offset:35840
	ds_read_b128 v[204:207], v182 offset:36864
	ds_read_b128 v[208:211], v182 offset:37888
	ds_read_b128 v[212:215], v182 offset:38912
	ds_read_b128 v[216:219], v182 offset:39936
	global_load_lds_dwordx4 v[220:221], off
	v_lshl_add_u64 v[220:221], s[24:25], 0, v[160:161]
	s_mov_b32 m0, s35
	s_nop 0
	global_load_lds_dwordx4 v[220:221], off
	s_waitcnt vmcnt(8)
	s_waitcnt lgkmcnt(0)
	s_barrier
	s_setprio 1
	s_waitcnt lgkmcnt(0)
	v_mfma_i32_16x16x64_i8 v[142:145], v[66:69], v[188:191], v[142:145]
	v_mfma_i32_16x16x64_i8 v[138:141], v[74:77], v[188:191], v[138:141]
	v_mfma_i32_16x16x64_i8 v[126:129], v[66:69], v[196:199], v[126:129]
	v_mfma_i32_16x16x64_i8 v[122:125], v[74:77], v[196:199], v[122:125]
	v_mfma_i32_16x16x64_i8 v[110:113], v[66:69], v[204:207], v[110:113]
	v_mfma_i32_16x16x64_i8 v[106:109], v[74:77], v[204:207], v[106:109]
	v_mfma_i32_16x16x64_i8 v[94:97], v[66:69], v[212:215], v[94:97]
	v_mfma_i32_16x16x64_i8 v[90:93], v[74:77], v[212:215], v[90:93]
	v_mfma_i32_16x16x64_i8 v[142:145], v[70:73], v[192:195], v[142:145]
	v_mfma_i32_16x16x64_i8 v[138:141], v[78:81], v[192:195], v[138:141]
	v_mfma_i32_16x16x64_i8 v[126:129], v[70:73], v[200:203], v[126:129]
	v_mfma_i32_16x16x64_i8 v[122:125], v[78:81], v[200:203], v[122:125]
	v_mfma_i32_16x16x64_i8 v[110:113], v[70:73], v[208:211], v[110:113]
	v_mfma_i32_16x16x64_i8 v[106:109], v[78:81], v[208:211], v[106:109]
	v_mfma_i32_16x16x64_i8 v[94:97], v[70:73], v[216:219], v[94:97]
	v_mfma_i32_16x16x64_i8 v[90:93], v[78:81], v[216:219], v[90:93]
	s_setprio 0
	s_setprio 1
	v_mfma_i32_16x16x64_i8 v[134:137], v[146:149], v[188:191], v[134:137]
	v_mfma_i32_16x16x64_i8 v[130:133], v[174:177], v[188:191], v[130:133]
	v_mfma_i32_16x16x64_i8 v[118:121], v[146:149], v[196:199], v[118:121]
	v_mfma_i32_16x16x64_i8 v[114:117], v[174:177], v[196:199], v[114:117]
	v_mfma_i32_16x16x64_i8 v[102:105], v[146:149], v[204:207], v[102:105]
	v_mfma_i32_16x16x64_i8 v[98:101], v[174:177], v[204:207], v[98:101]
	v_mfma_i32_16x16x64_i8 v[86:89], v[146:149], v[212:215], v[86:89]
	v_mfma_i32_16x16x64_i8 v[82:85], v[174:177], v[212:215], v[82:85]
	v_mfma_i32_16x16x64_i8 v[134:137], v[150:153], v[192:195], v[134:137]
	v_mfma_i32_16x16x64_i8 v[130:133], v[184:187], v[192:195], v[130:133]
	v_mfma_i32_16x16x64_i8 v[118:121], v[150:153], v[200:203], v[118:121]
	v_mfma_i32_16x16x64_i8 v[114:117], v[184:187], v[200:203], v[114:117]
	v_mfma_i32_16x16x64_i8 v[102:105], v[150:153], v[208:211], v[102:105]
	v_mfma_i32_16x16x64_i8 v[98:101], v[184:187], v[208:211], v[98:101]
	v_mfma_i32_16x16x64_i8 v[86:89], v[150:153], v[216:219], v[86:89]
	v_mfma_i32_16x16x64_i8 v[82:85], v[184:187], v[216:219], v[82:85]
	s_setprio 0
	s_barrier
; #define PG8_STAGE(bufoff, gbase, voff) do { _Pragma("unroll") for (int _i = 0; _i < 2; ++_i) \
;         __builtin_amdgcn_global_load_lds((const unsigned*)((const char*)(gbase) + (voff)[_i]), (LAS unsigned*)(lds + (bufoff) + ldsw + _i * 8192), 16, 0, 0); } while (0)
; #define PG8_LDA(dst, b, h) do { _Pragma("unroll") for (int m = 0; m < 4; ++m) _Pragma("unroll") for (int k = 0; k < 2; ++k) dst[m][k] = *(const LAS bf16x8*)(lds + PG8_SA(b, h) + aoff + m * 2048 + k * 1024); } while (0)
; #define PG8_WAIT_V(n) asm volatile("s_waitcnt vmcnt(" #n ")" ::: "memory")
; #define PG8_WAIT_L(n) asm volatile("s_waitcnt lgkmcnt(" #n ")" ::: "memory")
; #define PG8_BAR __builtin_amdgcn_s_barrier()
; #define PG8_SCHED __builtin_amdgcn_sched_barrier(0)
; template <class Epi, class Sched, bool I8 = false>
; __device__ __forceinline__ void gemm_phase(LAS unsigned char* lds, const Gemm g, const Sched& S, const Epi& E) {
;     ...
;             PG8_LDA(At, 1, 1); PG8_STAGE(PG8_SB(1, 0), b3, voffB); PG8_STAGE(PG8_SB(1, 1), b3 + hstepB, voffB); PG8_STAGE(PG8_SA(1, 0), a3, voffA);
;             PG8_WAIT_V(8); PG8_WAIT_L(0); PG8_BAR; PG8_MMA(1, 0, At, B0); PG8_MMA(1, 1, At, B1); PG8_BAR; PG8_SCHED;
;         }
;         if (wr == 0) PG8_BAR;
	s_add_u32 s24, s22, 0x8000
	s_addc_u32 s25, s23, 0
	s_add_i32 s50, s50, s30
	v_lshl_add_u64 v[220:221], s[24:25], 0, v[158:159]
	s_mov_b32 m0, s50
	ds_read_b128 v[188:191], v182 offset:49152
	ds_read_b128 v[192:195], v182 offset:50176
	ds_read_b128 v[196:199], v182 offset:51200
	ds_read_b128 v[200:203], v182 offset:52224
	ds_read_b128 v[204:207], v182 offset:53248
	ds_read_b128 v[208:211], v182 offset:54272
	ds_read_b128 v[212:215], v182 offset:55296
	ds_read_b128 v[216:219], v182 offset:56320
	global_load_lds_dwordx4 v[220:221], off
	s_add_i32 m0, s50, 0x2000
	s_add_u32 s22, s22, 0xc000
	v_lshl_add_u64 v[220:221], s[24:25], 0, v[162:163]
	s_addc_u32 s23, s23, 0
	s_add_i32 s24, s51, s30
	global_load_lds_dwordx4 v[220:221], off
	v_lshl_add_u64 v[220:221], s[22:23], 0, v[158:159]
	s_mov_b32 m0, s24
	s_nop 0
	global_load_lds_dwordx4 v[220:221], off
	v_lshl_add_u64 v[220:221], s[22:23], 0, v[162:163]
	s_add_i32 m0, s24, 0x2000
	s_nop 0
	global_load_lds_dwordx4 v[220:221], off
	v_lshl_add_u64 v[220:221], s[20:21], 0, v[156:157]
	s_mov_b32 m0, s37
	s_nop 0
	global_load_lds_dwordx4 v[220:221], off
	s_waitcnt vmcnt(7)
	s_waitcnt lgkmcnt(0)
	s_barrier
	s_setprio 1
	s_waitcnt lgkmcnt(0)
	v_mfma_i32_16x16x64_i8 v[62:65], v[66:69], v[188:191], v[62:65]
	v_mfma_i32_16x16x64_i8 v[58:61], v[74:77], v[188:191], v[58:61]
	v_mfma_i32_16x16x64_i8 v[46:49], v[66:69], v[196:199], v[46:49]
	v_mfma_i32_16x16x64_i8 v[42:45], v[74:77], v[196:199], v[42:45]
	v_mfma_i32_16x16x64_i8 v[30:33], v[66:69], v[204:207], v[30:33]
	v_mfma_i32_16x16x64_i8 v[26:29], v[74:77], v[204:207], v[26:29]
	v_mfma_i32_16x16x64_i8 v[14:17], v[66:69], v[212:215], v[14:17]
	v_mfma_i32_16x16x64_i8 v[10:13], v[74:77], v[212:215], v[10:13]
	v_mfma_i32_16x16x64_i8 v[62:65], v[70:73], v[192:195], v[62:65]
	v_mfma_i32_16x16x64_i8 v[58:61], v[78:81], v[192:195], v[58:61]
	v_mfma_i32_16x16x64_i8 v[46:49], v[70:73], v[200:203], v[46:49]
	v_mfma_i32_16x16x64_i8 v[42:45], v[78:81], v[200:203], v[42:45]
	v_mfma_i32_16x16x64_i8 v[30:33], v[70:73], v[208:211], v[30:33]
	v_mfma_i32_16x16x64_i8 v[26:29], v[78:81], v[208:211], v[26:29]
	v_mfma_i32_16x16x64_i8 v[14:17], v[70:73], v[216:219], v[14:17]
	v_mfma_i32_16x16x64_i8 v[10:13], v[78:81], v[216:219], v[10:13]
	s_setprio 0
	s_setprio 1
	v_mfma_i32_16x16x64_i8 v[54:57], v[146:149], v[188:191], v[54:57]
	v_mfma_i32_16x16x64_i8 v[50:53], v[174:177], v[188:191], v[50:53]
	v_mfma_i32_16x16x64_i8 v[38:41], v[146:149], v[196:199], v[38:41]
	v_mfma_i32_16x16x64_i8 v[34:37], v[174:177], v[196:199], v[34:37]
	v_mfma_i32_16x16x64_i8 v[22:25], v[146:149], v[204:207], v[22:25]
	v_mfma_i32_16x16x64_i8 v[18:21], v[174:177], v[204:207], v[18:21]
	v_mfma_i32_16x16x64_i8 v[6:9], v[146:149], v[212:215], v[6:9]
	v_mfma_i32_16x16x64_i8 v[2:5], v[174:177], v[212:215], v[2:5]
	v_mfma_i32_16x16x64_i8 v[54:57], v[150:153], v[192:195], v[54:57]
	v_mfma_i32_16x16x64_i8 v[50:53], v[184:187], v[192:195], v[50:53]
	v_mfma_i32_16x16x64_i8 v[38:41], v[150:153], v[200:203], v[38:41]
	v_mfma_i32_16x16x64_i8 v[34:37], v[184:187], v[200:203], v[34:37]
	v_mfma_i32_16x16x64_i8 v[22:25], v[150:153], v[208:211], v[22:25]
	v_mfma_i32_16x16x64_i8 v[18:21], v[184:187], v[208:211], v[18:21]
	v_mfma_i32_16x16x64_i8 v[6:9], v[150:153], v[216:219], v[6:9]
	v_mfma_i32_16x16x64_i8 v[2:5], v[184:187], v[216:219], v[2:5]
	s_setprio 0
	s_barrier
	s_add_i32 s49, s49, 2
	s_add_u32 s18, s18, 0x10000
	s_addc_u32 s19, s19, 0
	s_add_u32 s47, s47, 0x10000
	s_addc_u32 s48, s48, 0
	s_cmpk_gt_u32 s49, 0x53
	s_cbranch_scc0 .LBB0_1393
	s_and_b64 vcc, exec, s[14:15]
	s_cbranch_vccz .LBB0_1396
	s_barrier

; #define PG8_STAGE(bufoff, gbase, voff) do { _Pragma("unroll") for (int _i = 0; _i < 2; ++_i) \
;         __builtin_amdgcn_global_load_lds((const unsigned*)((const char*)(gbase) + (voff)[_i]), (LAS unsigned*)(lds + (bufoff) + ldsw + _i * 8192), 16, 0, 0); } while (0)
; #define PG8_LDA(dst, b, h) do { _Pragma("unroll") for (int m = 0; m < 4; ++m) _Pragma("unroll") for (int k = 0; k < 2; ++k) dst[m][k] = *(const LAS bf16x8*)(lds + PG8_SA(b, h) + aoff + m * 2048 + k * 1024); } while (0)
; #define PG8_LDB(dst, b, h) do { _Pragma("unroll") for (int n = 0; n < 2; ++n) _Pragma("unroll") for (int k = 0; k < 2; ++k) dst[n][k] = *(const LAS bf16x8*)(lds + PG8_SB(b, h) + boff + n * 2048 + k * 1024); } while (0)
; #define PG8_WAIT_V(n) asm volatile("s_waitcnt vmcnt(" #n ")" ::: "memory")
; #define PG8_WAIT_L(n) asm volatile("s_waitcnt lgkmcnt(" #n ")" ::: "memory")
; #define PG8_BAR __builtin_amdgcn_s_barrier()
; #define PG8_SCHED __builtin_amdgcn_sched_barrier(0)
; template <class Epi, class Sched, bool I8 = false>
; __device__ __forceinline__ void gemm_phase(LAS unsigned char* lds, const Gemm g, const Sched& S, const Epi& E) {
;     ...
;             const char* a1 = cA + (size_t)(t + 1) * kstep;
;             const char* a2 = last ? nA : cA + (size_t)(t + 2) * kstep; const char* b2 = last ? nB : cB + (size_t)(t + 2) * kstep;
;             const char* a3 = a2 + kstep; const char* b3 = b2 + kstep;
;             PG8_LDB(B0, 0, 0); PG8_LDB(B1, 0, 1); PG8_SCHED; PG8_LDA(At, 0, 0); PG8_STAGE(PG8_SA(1, 1), a1 + hstepA, voffA);
;             PG8_WAIT_V(8); PG8_WAIT_L(0); PG8_BAR; PG8_MMA(0, 0, At, B0); PG8_MMA(0, 1, At, B1); PG8_BAR; PG8_SCHED;
;             PG8_LDA(At, 0, 1); PG8_STAGE(PG8_SB(0, 0), b2, voffB); PG8_STAGE(PG8_SB(0, 1), b2 + hstepB, voffB); PG8_STAGE(PG8_SA(0, 0), a2, voffA);
;             PG8_WAIT_V(8); PG8_WAIT_L(0); PG8_BAR; PG8_MMA(1, 0, At, B0); PG8_MMA(1, 1, At, B1); PG8_BAR; PG8_SCHED;
.LBB0_1482:
	ds_read_b128 v[152:155], v182
	ds_read_b128 v[156:159], v182 offset:1024
	ds_read_b128 v[160:163], v182 offset:2048
	ds_read_b128 v[164:167], v182 offset:3072
	ds_read_b128 v[168:171], v183
	ds_read_b128 v[172:175], v183 offset:1024
	ds_read_b128 v[176:179], v183 offset:2048
	ds_read_b128 v[186:189], v183 offset:3072
	s_add_u32 s38, s8, 0x4000
	s_addc_u32 s39, s9, 0
	s_cmp_eq_u32 s47, 60
	s_cselect_b32 s42, s31, s38
	s_cselect_b32 s43, s7, s39
	s_cselect_b32 s40, s44, s45
	s_cselect_b32 s41, s29, s46
	s_add_u32 s38, s42, 0x8000
	s_addc_u32 s39, s43, 0
	s_sub_u32 s98, s8, 0x4000
	s_subb_u32 s99, s9, 0
	v_lshl_add_u64 v[222:223], s[98:99], 0, v[134:135]
	s_mov_b32 m0, s59
	s_nop 0
	global_load_lds_dwordx4 v[222:223], off
	v_lshl_add_u64 v[222:223], s[8:9], 0, v[144:145]
	s_add_i32 m0, s33, 0xc000
	ds_read_b128 v[190:193], v184
	ds_read_b128 v[194:197], v184 offset:1024
	ds_read_b128 v[198:201], v184 offset:2048
	ds_read_b128 v[202:205], v184 offset:3072
	ds_read_b128 v[206:209], v184 offset:4096
	ds_read_b128 v[210:213], v184 offset:5120
	ds_read_b128 v[214:217], v184 offset:6144
	ds_read_b128 v[218:221], v184 offset:7168
	global_load_lds_dwordx4 v[222:223], off
	v_lshl_add_u64 v[222:223], s[8:9], 0, v[146:147]
	s_add_i32 m0, s33, 0xe000
	s_nop 0
	global_load_lds_dwordx4 v[222:223], off
	s_waitcnt vmcnt(8)
	s_waitcnt lgkmcnt(0)
	s_barrier
	s_setprio 1
	s_waitcnt lgkmcnt(0)
	v_mfma_f32_16x16x32_bf16 v[126:129], v[152:155], v[190:193], v[126:129]
	v_mfma_f32_16x16x32_bf16 v[122:125], v[160:163], v[190:193], v[122:125]
	v_mfma_f32_16x16x32_bf16 v[110:113], v[152:155], v[198:201], v[110:113]
	v_mfma_f32_16x16x32_bf16 v[106:109], v[160:163], v[198:201], v[106:109]
	v_mfma_f32_16x16x32_bf16 v[94:97], v[152:155], v[206:209], v[94:97]
	v_mfma_f32_16x16x32_bf16 v[90:93], v[160:163], v[206:209], v[90:93]
	v_mfma_f32_16x16x32_bf16 v[78:81], v[152:155], v[214:217], v[78:81]
	v_mfma_f32_16x16x32_bf16 v[74:77], v[160:163], v[214:217], v[74:77]
	v_mfma_f32_16x16x32_bf16 v[126:129], v[156:159], v[194:197], v[126:129]
	v_mfma_f32_16x16x32_bf16 v[122:125], v[164:167], v[194:197], v[122:125]
	v_mfma_f32_16x16x32_bf16 v[110:113], v[156:159], v[202:205], v[110:113]
	v_mfma_f32_16x16x32_bf16 v[106:109], v[164:167], v[202:205], v[106:109]
	v_mfma_f32_16x16x32_bf16 v[94:97], v[156:159], v[210:213], v[94:97]
	v_mfma_f32_16x16x32_bf16 v[90:93], v[164:167], v[210:213], v[90:93]
	v_mfma_f32_16x16x32_bf16 v[78:81], v[156:159], v[218:221], v[78:81]
	v_mfma_f32_16x16x32_bf16 v[74:77], v[164:167], v[218:221], v[74:77]
	s_setprio 0
	s_setprio 1
	v_mfma_f32_16x16x32_bf16 v[118:121], v[168:171], v[190:193], v[118:121]
	v_mfma_f32_16x16x32_bf16 v[114:117], v[176:179], v[190:193], v[114:117]
	v_mfma_f32_16x16x32_bf16 v[102:105], v[168:171], v[198:201], v[102:105]
	v_mfma_f32_16x16x32_bf16 v[98:101], v[176:179], v[198:201], v[98:101]
	v_mfma_f32_16x16x32_bf16 v[86:89], v[168:171], v[206:209], v[86:89]
	v_mfma_f32_16x16x32_bf16 v[82:85], v[176:179], v[206:209], v[82:85]
	v_mfma_f32_16x16x32_bf16 v[70:73], v[168:171], v[214:217], v[70:73]
	v_mfma_f32_16x16x32_bf16 v[66:69], v[176:179], v[214:217], v[66:69]
	v_mfma_f32_16x16x32_bf16 v[118:121], v[172:175], v[194:197], v[118:121]
	v_mfma_f32_16x16x32_bf16 v[114:117], v[186:189], v[194:197], v[114:117]
	v_mfma_f32_16x16x32_bf16 v[102:105], v[172:175], v[202:205], v[102:105]
	v_mfma_f32_16x16x32_bf16 v[98:101], v[186:189], v[202:205], v[98:101]
	v_mfma_f32_16x16x32_bf16 v[86:89], v[172:175], v[210:213], v[86:89]
	v_mfma_f32_16x16x32_bf16 v[82:85], v[186:189], v[210:213], v[82:85]
	v_mfma_f32_16x16x32_bf16 v[70:73], v[172:175], v[218:221], v[70:73]
	v_mfma_f32_16x16x32_bf16 v[66:69], v[186:189], v[218:221], v[66:69]
	s_setprio 0
	s_barrier
	s_add_i32 s48, s63, s25
	v_lshl_add_u64 v[222:223], s[40:41], 0, v[132:133]
	s_mov_b32 m0, s48
	ds_read_b128 v[190:193], v184 offset:16384
	ds_read_b128 v[194:197], v184 offset:17408
	ds_read_b128 v[198:201], v184 offset:18432
	ds_read_b128 v[202:205], v184 offset:19456
	ds_read_b128 v[206:209], v184 offset:20480
	ds_read_b128 v[210:213], v184 offset:21504
	ds_read_b128 v[214:217], v184 offset:22528
	ds_read_b128 v[218:221], v184 offset:23552
	global_load_lds_dwordx4 v[222:223], off
	s_add_i32 m0, s48, 0x2000
	s_add_u32 s48, s40, 0x4000
	v_lshl_add_u64 v[222:223], s[40:41], 0, v[136:137]
	s_addc_u32 s49, s41, 0
	s_add_i32 s50, s64, s25
	global_load_lds_dwordx4 v[222:223], off
	v_lshl_add_u64 v[222:223], s[48:49], 0, v[132:133]
	s_mov_b32 m0, s50
	s_nop 0
	global_load_lds_dwordx4 v[222:223], off
	v_lshl_add_u64 v[222:223], s[48:49], 0, v[136:137]
	s_add_i32 m0, s50, 0x2000
	s_nop 0
	global_load_lds_dwordx4 v[222:223], off
	v_lshl_add_u64 v[222:223], s[42:43], 0, v[130:131]
	s_mov_b32 m0, s33
	s_nop 0
	global_load_lds_dwordx4 v[222:223], off
	s_waitcnt vmcnt(7)
	s_waitcnt lgkmcnt(0)
	s_barrier
; #define PG8_STAGE(bufoff, gbase, voff) do { _Pragma("unroll") for (int _i = 0; _i < 2; ++_i) \
;         __builtin_amdgcn_global_load_lds((const unsigned*)((const char*)(gbase) + (voff)[_i]), (LAS unsigned*)(lds + (bufoff) + ldsw + _i * 8192), 16, 0, 0); } while (0)
; #define PG8_LDA(dst, b, h) do { _Pragma("unroll") for (int m = 0; m < 4; ++m) _Pragma("unroll") for (int k = 0; k < 2; ++k) dst[m][k] = *(const LAS bf16x8*)(lds + PG8_SA(b, h) + aoff + m * 2048 + k * 1024); } while (0)
; #define PG8_LDB(dst, b, h) do { _Pragma("unroll") for (int n = 0; n < 2; ++n) _Pragma("unroll") for (int k = 0; k < 2; ++k) dst[n][k] = *(const LAS bf16x8*)(lds + PG8_SB(b, h) + boff + n * 2048 + k * 1024); } while (0)
; #define PG8_WAIT_V(n) asm volatile("s_waitcnt vmcnt(" #n ")" ::: "memory")
; #define PG8_WAIT_L(n) asm volatile("s_waitcnt lgkmcnt(" #n ")" ::: "memory")
; #define PG8_BAR __builtin_amdgcn_s_barrier()
; #define PG8_SCHED __builtin_amdgcn_sched_barrier(0)
; template <class Epi, class Sched, bool I8 = false>
; __device__ __forceinline__ void gemm_phase(LAS unsigned char* lds, const Gemm g, const Sched& S, const Epi& E) {
;     ...
;             PG8_WAIT_V(8); PG8_WAIT_L(0); PG8_BAR; PG8_MMA(1, 0, At, B0); PG8_MMA(1, 1, At, B1); PG8_BAR; PG8_SCHED;
;             PG8_LDB(B0, 1, 0); PG8_LDB(B1, 1, 1); PG8_SCHED; PG8_LDA(At, 1, 0); PG8_STAGE(PG8_SA(0, 1), a2 + hstepA, voffA);
;             PG8_WAIT_V(8); PG8_WAIT_L(0); PG8_BAR; PG8_MMA(0, 0, At, B0); PG8_MMA(0, 1, At, B1); PG8_BAR; PG8_SCHED;
	s_setprio 1
	s_waitcnt lgkmcnt(0)
	v_mfma_f32_16x16x32_bf16 v[62:65], v[152:155], v[190:193], v[62:65]
	v_mfma_f32_16x16x32_bf16 v[58:61], v[160:163], v[190:193], v[58:61]
	v_mfma_f32_16x16x32_bf16 v[46:49], v[152:155], v[198:201], v[46:49]
	v_mfma_f32_16x16x32_bf16 v[42:45], v[160:163], v[198:201], v[42:45]
	v_mfma_f32_16x16x32_bf16 v[30:33], v[152:155], v[206:209], v[30:33]
	v_mfma_f32_16x16x32_bf16 v[26:29], v[160:163], v[206:209], v[26:29]
	v_mfma_f32_16x16x32_bf16 v[14:17], v[152:155], v[214:217], v[14:17]
	v_mfma_f32_16x16x32_bf16 v[10:13], v[160:163], v[214:217], v[10:13]
	v_mfma_f32_16x16x32_bf16 v[62:65], v[156:159], v[194:197], v[62:65]
	v_mfma_f32_16x16x32_bf16 v[58:61], v[164:167], v[194:197], v[58:61]
	v_mfma_f32_16x16x32_bf16 v[46:49], v[156:159], v[202:205], v[46:49]
	v_mfma_f32_16x16x32_bf16 v[42:45], v[164:167], v[202:205], v[42:45]
	v_mfma_f32_16x16x32_bf16 v[30:33], v[156:159], v[210:213], v[30:33]
	v_mfma_f32_16x16x32_bf16 v[26:29], v[164:167], v[210:213], v[26:29]
	v_mfma_f32_16x16x32_bf16 v[14:17], v[156:159], v[218:221], v[14:17]
	v_mfma_f32_16x16x32_bf16 v[10:13], v[164:167], v[218:221], v[10:13]
	s_setprio 0
	s_setprio 1
	v_mfma_f32_16x16x32_bf16 v[54:57], v[168:171], v[190:193], v[54:57]
	v_mfma_f32_16x16x32_bf16 v[50:53], v[176:179], v[190:193], v[50:53]
	v_mfma_f32_16x16x32_bf16 v[38:41], v[168:171], v[198:201], v[38:41]
	v_mfma_f32_16x16x32_bf16 v[34:37], v[176:179], v[198:201], v[34:37]
	v_mfma_f32_16x16x32_bf16 v[22:25], v[168:171], v[206:209], v[22:25]
	v_mfma_f32_16x16x32_bf16 v[18:21], v[176:179], v[206:209], v[18:21]
	v_mfma_f32_16x16x32_bf16 v[6:9], v[168:171], v[214:217], v[6:9]
	v_mfma_f32_16x16x32_bf16 v[2:5], v[176:179], v[214:217], v[2:5]
	v_mfma_f32_16x16x32_bf16 v[54:57], v[172:175], v[194:197], v[54:57]
	v_mfma_f32_16x16x32_bf16 v[50:53], v[186:189], v[194:197], v[50:53]
	v_mfma_f32_16x16x32_bf16 v[38:41], v[172:175], v[202:205], v[38:41]
	v_mfma_f32_16x16x32_bf16 v[34:37], v[186:189], v[202:205], v[34:37]
	v_mfma_f32_16x16x32_bf16 v[22:25], v[172:175], v[210:213], v[22:25]
	v_mfma_f32_16x16x32_bf16 v[18:21], v[186:189], v[210:213], v[18:21]
	v_mfma_f32_16x16x32_bf16 v[6:9], v[172:175], v[218:221], v[6:9]
	v_mfma_f32_16x16x32_bf16 v[2:5], v[186:189], v[218:221], v[2:5]
	s_setprio 0
	s_barrier
	s_add_i32 s48, 0, 0x18000
	v_add_u32_e32 v138, s48, v181
	s_add_i32 s49, 0, 0x1c000
	ds_read_b128 v[152:155], v138
	ds_read_b128 v[156:159], v138 offset:1024
	ds_read_b128 v[160:163], v138 offset:2048
	ds_read_b128 v[164:167], v138 offset:3072
	v_add_u32_e32 v138, s49, v181
	ds_read_b128 v[168:171], v138
	ds_read_b128 v[172:175], v138 offset:1024
	ds_read_b128 v[176:179], v138 offset:2048
	ds_read_b128 v[186:189], v138 offset:3072
	v_lshl_add_u64 v[222:223], s[42:43], 0, v[134:135]
	s_mov_b32 m0, s52
	s_nop 0
	global_load_lds_dwordx4 v[222:223], off
	s_add_u32 s42, s42, 0x4000
	s_addc_u32 s43, s43, 0
	s_mov_b32 m0, s53
	v_lshl_add_u64 v[222:223], s[42:43], 0, v[130:131]
	ds_read_b128 v[190:193], v184 offset:32768
	ds_read_b128 v[194:197], v184 offset:33792
	ds_read_b128 v[198:201], v184 offset:34816
	ds_read_b128 v[202:205], v184 offset:35840
	ds_read_b128 v[206:209], v184 offset:36864
	ds_read_b128 v[210:213], v184 offset:37888
	ds_read_b128 v[214:217], v184 offset:38912
	ds_read_b128 v[218:221], v184 offset:39936
	global_load_lds_dwordx4 v[222:223], off
	v_lshl_add_u64 v[222:223], s[42:43], 0, v[134:135]
	s_mov_b32 m0, s54
	s_nop 0
	global_load_lds_dwordx4 v[222:223], off
	s_waitcnt vmcnt(8)
	s_waitcnt lgkmcnt(0)
	s_barrier
	s_setprio 1
	s_waitcnt lgkmcnt(0)
	v_mfma_f32_16x16x32_bf16 v[126:129], v[152:155], v[190:193], v[126:129]
	v_mfma_f32_16x16x32_bf16 v[122:125], v[160:163], v[190:193], v[122:125]
	v_mfma_f32_16x16x32_bf16 v[110:113], v[152:155], v[198:201], v[110:113]
	v_mfma_f32_16x16x32_bf16 v[106:109], v[160:163], v[198:201], v[106:109]
	v_mfma_f32_16x16x32_bf16 v[94:97], v[152:155], v[206:209], v[94:97]
	v_mfma_f32_16x16x32_bf16 v[90:93], v[160:163], v[206:209], v[90:93]
	v_mfma_f32_16x16x32_bf16 v[78:81], v[152:155], v[214:217], v[78:81]
	v_mfma_f32_16x16x32_bf16 v[74:77], v[160:163], v[214:217], v[74:77]
	v_mfma_f32_16x16x32_bf16 v[126:129], v[156:159], v[194:197], v[126:129]
	v_mfma_f32_16x16x32_bf16 v[122:125], v[164:167], v[194:197], v[122:125]
	v_mfma_f32_16x16x32_bf16 v[110:113], v[156:159], v[202:205], v[110:113]
	v_mfma_f32_16x16x32_bf16 v[106:109], v[164:167], v[202:205], v[106:109]
	v_mfma_f32_16x16x32_bf16 v[94:97], v[156:159], v[210:213], v[94:97]
	v_mfma_f32_16x16x32_bf16 v[90:93], v[164:167], v[210:213], v[90:93]
	v_mfma_f32_16x16x32_bf16 v[78:81], v[156:159], v[218:221], v[78:81]
	v_mfma_f32_16x16x32_bf16 v[74:77], v[164:167], v[218:221], v[74:77]
	s_setprio 0
	s_setprio 1
	v_mfma_f32_16x16x32_bf16 v[118:121], v[168:171], v[190:193], v[118:121]
	v_mfma_f32_16x16x32_bf16 v[114:117], v[176:179], v[190:193], v[114:117]
	v_mfma_f32_16x16x32_bf16 v[102:105], v[168:171], v[198:201], v[102:105]
	v_mfma_f32_16x16x32_bf16 v[98:101], v[176:179], v[198:201], v[98:101]
	v_mfma_f32_16x16x32_bf16 v[86:89], v[168:171], v[206:209], v[86:89]
	v_mfma_f32_16x16x32_bf16 v[82:85], v[176:179], v[206:209], v[82:85]
	v_mfma_f32_16x16x32_bf16 v[70:73], v[168:171], v[214:217], v[70:73]
	v_mfma_f32_16x16x32_bf16 v[66:69], v[176:179], v[214:217], v[66:69]
	v_mfma_f32_16x16x32_bf16 v[118:121], v[172:175], v[194:197], v[118:121]
	v_mfma_f32_16x16x32_bf16 v[114:117], v[186:189], v[194:197], v[114:117]
	v_mfma_f32_16x16x32_bf16 v[102:105], v[172:175], v[202:205], v[102:105]
	v_mfma_f32_16x16x32_bf16 v[98:101], v[186:189], v[202:205], v[98:101]
	v_mfma_f32_16x16x32_bf16 v[86:89], v[172:175], v[210:213], v[86:89]
	v_mfma_f32_16x16x32_bf16 v[82:85], v[186:189], v[210:213], v[82:85]
	v_mfma_f32_16x16x32_bf16 v[70:73], v[172:175], v[218:221], v[70:73]
	v_mfma_f32_16x16x32_bf16 v[66:69], v[186:189], v[218:221], v[66:69]
	s_setprio 0
	s_barrier
; #define PG8_STAGE(bufoff, gbase, voff) do { _Pragma("unroll") for (int _i = 0; _i < 2; ++_i) \
;         __builtin_amdgcn_global_load_lds((const unsigned*)((const char*)(gbase) + (voff)[_i]), (LAS unsigned*)(lds + (bufoff) + ldsw + _i * 8192), 16, 0, 0); } while (0)
; #define PG8_LDA(dst, b, h) do { _Pragma("unroll") for (int m = 0; m < 4; ++m) _Pragma("unroll") for (int k = 0; k < 2; ++k) dst[m][k] = *(const LAS bf16x8*)(lds + PG8_SA(b, h) + aoff + m * 2048 + k * 1024); } while (0)
; #define PG8_WAIT_V(n) asm volatile("s_waitcnt vmcnt(" #n ")" ::: "memory")
; #define PG8_WAIT_L(n) asm volatile("s_waitcnt lgkmcnt(" #n ")" ::: "memory")
; #define PG8_BAR __builtin_amdgcn_s_barrier()
; #define PG8_SCHED __builtin_amdgcn_sched_barrier(0)
; template <class Epi, class Sched, bool I8 = false>
; __device__ __forceinline__ void gemm_phase(LAS unsigned char* lds, const Gemm g, const Sched& S, const Epi& E) {
;     ...
;             PG8_LDA(At, 1, 1); PG8_STAGE(PG8_SB(1, 0), b3, voffB); PG8_STAGE(PG8_SB(1, 1), b3 + hstepB, voffB); PG8_STAGE(PG8_SA(1, 0), a3, voffA);
;             PG8_WAIT_V(8); PG8_WAIT_L(0); PG8_BAR; PG8_MMA(1, 0, At, B0); PG8_MMA(1, 1, At, B1); PG8_BAR; PG8_SCHED;
;         }
;         if (wr == 0) PG8_BAR;
	s_add_u32 s42, s40, 0x8000
	s_addc_u32 s43, s41, 0
	s_add_i32 s48, s48, s25
	v_lshl_add_u64 v[222:223], s[42:43], 0, v[132:133]
	s_mov_b32 m0, s48
	ds_read_b128 v[190:193], v184 offset:49152
	ds_read_b128 v[194:197], v184 offset:50176
	ds_read_b128 v[198:201], v184 offset:51200
	ds_read_b128 v[202:205], v184 offset:52224
	ds_read_b128 v[206:209], v184 offset:53248
	ds_read_b128 v[210:213], v184 offset:54272
	ds_read_b128 v[214:217], v184 offset:55296
	ds_read_b128 v[218:221], v184 offset:56320
	global_load_lds_dwordx4 v[222:223], off
	s_add_i32 m0, s48, 0x2000
	s_add_u32 s40, s40, 0xc000
	v_lshl_add_u64 v[222:223], s[42:43], 0, v[136:137]
	s_addc_u32 s41, s41, 0
	s_add_i32 s42, s49, s25
	global_load_lds_dwordx4 v[222:223], off
	v_lshl_add_u64 v[222:223], s[40:41], 0, v[132:133]
	s_mov_b32 m0, s42
	s_nop 0
	global_load_lds_dwordx4 v[222:223], off
	v_lshl_add_u64 v[222:223], s[40:41], 0, v[136:137]
	s_add_i32 m0, s42, 0x2000
	s_nop 0
	global_load_lds_dwordx4 v[222:223], off
	v_lshl_add_u64 v[222:223], s[38:39], 0, v[130:131]
	s_mov_b32 m0, s58
	s_nop 0
	global_load_lds_dwordx4 v[222:223], off
	s_waitcnt vmcnt(7)
	s_waitcnt lgkmcnt(0)
	s_barrier
	s_setprio 1
	s_waitcnt lgkmcnt(0)
	v_mfma_f32_16x16x32_bf16 v[62:65], v[152:155], v[190:193], v[62:65]
	v_mfma_f32_16x16x32_bf16 v[58:61], v[160:163], v[190:193], v[58:61]
	v_mfma_f32_16x16x32_bf16 v[46:49], v[152:155], v[198:201], v[46:49]
	v_mfma_f32_16x16x32_bf16 v[42:45], v[160:163], v[198:201], v[42:45]
	v_mfma_f32_16x16x32_bf16 v[30:33], v[152:155], v[206:209], v[30:33]
	v_mfma_f32_16x16x32_bf16 v[26:29], v[160:163], v[206:209], v[26:29]
	v_mfma_f32_16x16x32_bf16 v[14:17], v[152:155], v[214:217], v[14:17]
	v_mfma_f32_16x16x32_bf16 v[10:13], v[160:163], v[214:217], v[10:13]
	v_mfma_f32_16x16x32_bf16 v[62:65], v[156:159], v[194:197], v[62:65]
	v_mfma_f32_16x16x32_bf16 v[58:61], v[164:167], v[194:197], v[58:61]
	v_mfma_f32_16x16x32_bf16 v[46:49], v[156:159], v[202:205], v[46:49]
	v_mfma_f32_16x16x32_bf16 v[42:45], v[164:167], v[202:205], v[42:45]
	v_mfma_f32_16x16x32_bf16 v[30:33], v[156:159], v[210:213], v[30:33]
	v_mfma_f32_16x16x32_bf16 v[26:29], v[164:167], v[210:213], v[26:29]
	v_mfma_f32_16x16x32_bf16 v[14:17], v[156:159], v[218:221], v[14:17]
	v_mfma_f32_16x16x32_bf16 v[10:13], v[164:167], v[218:221], v[10:13]
	s_setprio 0
	s_setprio 1
	v_mfma_f32_16x16x32_bf16 v[54:57], v[168:171], v[190:193], v[54:57]
	v_mfma_f32_16x16x32_bf16 v[50:53], v[176:179], v[190:193], v[50:53]
	v_mfma_f32_16x16x32_bf16 v[38:41], v[168:171], v[198:201], v[38:41]
	v_mfma_f32_16x16x32_bf16 v[34:37], v[176:179], v[198:201], v[34:37]
	v_mfma_f32_16x16x32_bf16 v[22:25], v[168:171], v[206:209], v[22:25]
	v_mfma_f32_16x16x32_bf16 v[18:21], v[176:179], v[206:209], v[18:21]
	v_mfma_f32_16x16x32_bf16 v[6:9], v[168:171], v[214:217], v[6:9]
	v_mfma_f32_16x16x32_bf16 v[2:5], v[176:179], v[214:217], v[2:5]
	v_mfma_f32_16x16x32_bf16 v[54:57], v[172:175], v[194:197], v[54:57]
	v_mfma_f32_16x16x32_bf16 v[50:53], v[186:189], v[194:197], v[50:53]
	v_mfma_f32_16x16x32_bf16 v[38:41], v[172:175], v[202:205], v[38:41]
	v_mfma_f32_16x16x32_bf16 v[34:37], v[186:189], v[202:205], v[34:37]
	v_mfma_f32_16x16x32_bf16 v[22:25], v[172:175], v[210:213], v[22:25]
	v_mfma_f32_16x16x32_bf16 v[18:21], v[186:189], v[210:213], v[18:21]
	v_mfma_f32_16x16x32_bf16 v[6:9], v[172:175], v[218:221], v[6:9]
	v_mfma_f32_16x16x32_bf16 v[2:5], v[186:189], v[218:221], v[2:5]
	s_setprio 0
	s_barrier
	s_add_i32 s47, s47, 2
	s_add_u32 s8, s8, 0x10000
	s_addc_u32 s9, s9, 0
	s_add_u32 s45, s45, 0x10000
	s_addc_u32 s46, s46, 0
	s_cmp_gt_u32 s47, 61
	s_cbranch_scc0 .LBB0_1482
	s_and_b64 vcc, exec, s[20:21]
	s_cbranch_vccz .LBB0_1485
	s_barrier

; #define PG8_STAGE(bufoff, gbase, voff) do { _Pragma("unroll") for (int _i = 0; _i < 2; ++_i) \
;         __builtin_amdgcn_global_load_lds((const unsigned*)((const char*)(gbase) + (voff)[_i]), (LAS unsigned*)(lds + (bufoff) + ldsw + _i * 8192), 16, 0, 0); } while (0)
; #define PG8_LDA(dst, b, h) do { _Pragma("unroll") for (int m = 0; m < 4; ++m) _Pragma("unroll") for (int k = 0; k < 2; ++k) dst[m][k] = *(const LAS bf16x8*)(lds + PG8_SA(b, h) + aoff + m * 2048 + k * 1024); } while (0)
; #define PG8_LDB(dst, b, h) do { _Pragma("unroll") for (int n = 0; n < 2; ++n) _Pragma("unroll") for (int k = 0; k < 2; ++k) dst[n][k] = *(const LAS bf16x8*)(lds + PG8_SB(b, h) + boff + n * 2048 + k * 1024); } while (0)
; #define PG8_WAIT_V(n) asm volatile("s_waitcnt vmcnt(" #n ")" ::: "memory")
; #define PG8_WAIT_L(n) asm volatile("s_waitcnt lgkmcnt(" #n ")" ::: "memory")
; #define PG8_BAR __builtin_amdgcn_s_barrier()
; #define PG8_SCHED __builtin_amdgcn_sched_barrier(0)
; template <class Epi, class Sched, bool I8 = false>
; __device__ __forceinline__ void gemm_phase(LAS unsigned char* lds, const Gemm g, const Sched& S, const Epi& E) {
;     ...
;             const char* a1 = cA + (size_t)(t + 1) * kstep;
;             const char* a2 = last ? nA : cA + (size_t)(t + 2) * kstep; const char* b2 = last ? nB : cB + (size_t)(t + 2) * kstep;
;             const char* a3 = a2 + kstep; const char* b3 = b2 + kstep;
;             PG8_LDB(B0, 0, 0); PG8_LDB(B1, 0, 1); PG8_SCHED; PG8_LDA(At, 0, 0); PG8_STAGE(PG8_SA(1, 1), a1 + hstepA, voffA);
;             PG8_WAIT_V(8); PG8_WAIT_L(0); PG8_BAR; PG8_MMA(0, 0, At, B0); PG8_MMA(0, 1, At, B1); PG8_BAR; PG8_SCHED;
;             PG8_LDA(At, 0, 1); PG8_STAGE(PG8_SB(0, 0), b2, voffB); PG8_STAGE(PG8_SB(0, 1), b2 + hstepB, voffB); PG8_STAGE(PG8_SA(0, 0), a2, voffA);
;             PG8_WAIT_V(8); PG8_WAIT_L(0); PG8_BAR; PG8_MMA(1, 0, At, B0); PG8_MMA(1, 1, At, B1); PG8_BAR; PG8_SCHED;
.LBB0_2685:
	ds_read_b128 v[130:133], v166
	ds_read_b128 v[134:137], v166 offset:1024
	ds_read_b128 v[158:161], v166 offset:2048
	ds_read_b128 v[170:173], v166 offset:3072
	ds_read_b128 v[174:177], v167
	ds_read_b128 v[178:181], v167 offset:1024
	ds_read_b128 v[182:185], v167 offset:2048
	ds_read_b128 v[186:189], v167 offset:3072
	s_add_u32 s12, s10, 0x4000
	s_addc_u32 s13, s11, 0
	s_cmp_eq_u32 s45, 4
	s_cselect_b32 s16, s40, s12
	s_cselect_b32 s17, s39, s13
	s_cselect_b32 s14, s42, s43
	s_cselect_b32 s15, s41, s44
	s_add_u32 s12, s16, 0x8000
	s_addc_u32 s13, s17, 0
	s_sub_u32 s98, s10, 0x4000
	s_subb_u32 s99, s11, 0
	v_lshl_add_u64 v[162:163], s[98:99], 0, v[140:141]
	s_mov_b32 m0, s34
	s_nop 0
	global_load_lds_dwordx4 v[162:163], off
	v_lshl_add_u64 v[162:163], s[10:11], 0, v[150:151]
	s_add_i32 m0, s26, 0xc000
	ds_read_b128 v[190:193], v168
	ds_read_b128 v[194:197], v168 offset:1024
	ds_read_b128 v[198:201], v168 offset:2048
	ds_read_b128 v[202:205], v168 offset:3072
	ds_read_b128 v[206:209], v168 offset:4096
	ds_read_b128 v[210:213], v168 offset:5120
	ds_read_b128 v[214:217], v168 offset:6144
	ds_read_b128 v[218:221], v168 offset:7168
	global_load_lds_dwordx4 v[162:163], off
	v_lshl_add_u64 v[162:163], s[10:11], 0, v[152:153]
	s_add_i32 m0, s26, 0xe000
	s_nop 0
	global_load_lds_dwordx4 v[162:163], off
	s_waitcnt vmcnt(8)
	s_waitcnt lgkmcnt(0)
	s_barrier
	s_setprio 1
	s_waitcnt lgkmcnt(0)
	v_mfma_f32_16x16x32_bf16 v[126:129], v[130:133], v[190:193], v[126:129]
	v_mfma_f32_16x16x32_bf16 v[122:125], v[158:161], v[190:193], v[122:125]
	v_mfma_f32_16x16x32_bf16 v[118:121], v[130:133], v[198:201], v[118:121]
	v_mfma_f32_16x16x32_bf16 v[114:117], v[158:161], v[198:201], v[114:117]
	v_mfma_f32_16x16x32_bf16 v[110:113], v[130:133], v[206:209], v[110:113]
	v_mfma_f32_16x16x32_bf16 v[106:109], v[158:161], v[206:209], v[106:109]
	v_mfma_f32_16x16x32_bf16 v[102:105], v[130:133], v[214:217], v[102:105]
	v_mfma_f32_16x16x32_bf16 v[98:101], v[158:161], v[214:217], v[98:101]
	v_mfma_f32_16x16x32_bf16 v[126:129], v[134:137], v[194:197], v[126:129]
	v_mfma_f32_16x16x32_bf16 v[122:125], v[170:173], v[194:197], v[122:125]
	v_mfma_f32_16x16x32_bf16 v[118:121], v[134:137], v[202:205], v[118:121]
	v_mfma_f32_16x16x32_bf16 v[114:117], v[170:173], v[202:205], v[114:117]
	v_mfma_f32_16x16x32_bf16 v[110:113], v[134:137], v[210:213], v[110:113]
	v_mfma_f32_16x16x32_bf16 v[106:109], v[170:173], v[210:213], v[106:109]
	v_mfma_f32_16x16x32_bf16 v[102:105], v[134:137], v[218:221], v[102:105]
	v_mfma_f32_16x16x32_bf16 v[98:101], v[170:173], v[218:221], v[98:101]
	s_setprio 0
	s_setprio 1
	v_mfma_f32_16x16x32_bf16 v[62:65], v[174:177], v[190:193], v[62:65]
	v_mfma_f32_16x16x32_bf16 v[58:61], v[182:185], v[190:193], v[58:61]
	v_mfma_f32_16x16x32_bf16 v[54:57], v[174:177], v[198:201], v[54:57]
	v_mfma_f32_16x16x32_bf16 v[50:53], v[182:185], v[198:201], v[50:53]
	v_mfma_f32_16x16x32_bf16 v[46:49], v[174:177], v[206:209], v[46:49]
	v_mfma_f32_16x16x32_bf16 v[42:45], v[182:185], v[206:209], v[42:45]
	v_mfma_f32_16x16x32_bf16 v[38:41], v[174:177], v[214:217], v[38:41]
	v_mfma_f32_16x16x32_bf16 v[34:37], v[182:185], v[214:217], v[34:37]
	v_mfma_f32_16x16x32_bf16 v[62:65], v[178:181], v[194:197], v[62:65]
	v_mfma_f32_16x16x32_bf16 v[58:61], v[186:189], v[194:197], v[58:61]
	v_mfma_f32_16x16x32_bf16 v[54:57], v[178:181], v[202:205], v[54:57]
	v_mfma_f32_16x16x32_bf16 v[50:53], v[186:189], v[202:205], v[50:53]
	v_mfma_f32_16x16x32_bf16 v[46:49], v[178:181], v[210:213], v[46:49]
	v_mfma_f32_16x16x32_bf16 v[42:45], v[186:189], v[210:213], v[42:45]
	v_mfma_f32_16x16x32_bf16 v[38:41], v[178:181], v[218:221], v[38:41]
	v_mfma_f32_16x16x32_bf16 v[34:37], v[186:189], v[218:221], v[34:37]
	s_setprio 0
	s_barrier
	s_add_i32 s46, s62, s22
	v_lshl_add_u64 v[162:163], s[14:15], 0, v[142:143]
	s_mov_b32 m0, s46
	ds_read_b128 v[190:193], v168 offset:16384
	ds_read_b128 v[194:197], v168 offset:17408
	ds_read_b128 v[198:201], v168 offset:18432
	ds_read_b128 v[202:205], v168 offset:19456
	ds_read_b128 v[206:209], v168 offset:20480
	ds_read_b128 v[210:213], v168 offset:21504
	ds_read_b128 v[214:217], v168 offset:22528
	ds_read_b128 v[218:221], v168 offset:23552
	global_load_lds_dwordx4 v[162:163], off
	s_add_i32 m0, s46, 0x2000
	s_add_u32 s46, s14, 0x4000
	v_lshl_add_u64 v[162:163], s[14:15], 0, v[138:139]
	s_addc_u32 s47, s15, 0
	s_add_i32 s48, s35, s22
	global_load_lds_dwordx4 v[162:163], off
	v_lshl_add_u64 v[162:163], s[46:47], 0, v[142:143]
	s_mov_b32 m0, s48
	s_nop 0
	global_load_lds_dwordx4 v[162:163], off
	v_lshl_add_u64 v[162:163], s[46:47], 0, v[138:139]
	s_add_i32 m0, s48, 0x2000
	s_nop 0
	global_load_lds_dwordx4 v[162:163], off
	v_lshl_add_u64 v[162:163], s[16:17], 0, v[144:145]
	s_mov_b32 m0, s26
	s_nop 0
	global_load_lds_dwordx4 v[162:163], off
	s_waitcnt vmcnt(7)
	s_waitcnt lgkmcnt(0)
	s_barrier
; #define PG8_STAGE(bufoff, gbase, voff) do { _Pragma("unroll") for (int _i = 0; _i < 2; ++_i) \
;         __builtin_amdgcn_global_load_lds((const unsigned*)((const char*)(gbase) + (voff)[_i]), (LAS unsigned*)(lds + (bufoff) + ldsw + _i * 8192), 16, 0, 0); } while (0)
; #define PG8_LDA(dst, b, h) do { _Pragma("unroll") for (int m = 0; m < 4; ++m) _Pragma("unroll") for (int k = 0; k < 2; ++k) dst[m][k] = *(const LAS bf16x8*)(lds + PG8_SA(b, h) + aoff + m * 2048 + k * 1024); } while (0)
; #define PG8_LDB(dst, b, h) do { _Pragma("unroll") for (int n = 0; n < 2; ++n) _Pragma("unroll") for (int k = 0; k < 2; ++k) dst[n][k] = *(const LAS bf16x8*)(lds + PG8_SB(b, h) + boff + n * 2048 + k * 1024); } while (0)
; #define PG8_WAIT_V(n) asm volatile("s_waitcnt vmcnt(" #n ")" ::: "memory")
; #define PG8_WAIT_L(n) asm volatile("s_waitcnt lgkmcnt(" #n ")" ::: "memory")
; #define PG8_BAR __builtin_amdgcn_s_barrier()
; #define PG8_SCHED __builtin_amdgcn_sched_barrier(0)
; template <class Epi, class Sched, bool I8 = false>
; __device__ __forceinline__ void gemm_phase(LAS unsigned char* lds, const Gemm g, const Sched& S, const Epi& E) {
;     ...
;             PG8_WAIT_V(8); PG8_WAIT_L(0); PG8_BAR; PG8_MMA(1, 0, At, B0); PG8_MMA(1, 1, At, B1); PG8_BAR; PG8_SCHED;
;             PG8_LDB(B0, 1, 0); PG8_LDB(B1, 1, 1); PG8_SCHED; PG8_LDA(At, 1, 0); PG8_STAGE(PG8_SA(0, 1), a2 + hstepA, voffA);
;             PG8_WAIT_V(8); PG8_WAIT_L(0); PG8_BAR; PG8_MMA(0, 0, At, B0); PG8_MMA(0, 1, At, B1); PG8_BAR; PG8_SCHED;
	s_setprio 1
	s_waitcnt lgkmcnt(0)
	v_mfma_f32_16x16x32_bf16 v[94:97], v[130:133], v[190:193], v[94:97]
	v_mfma_f32_16x16x32_bf16 v[90:93], v[158:161], v[190:193], v[90:93]
	v_mfma_f32_16x16x32_bf16 v[86:89], v[130:133], v[198:201], v[86:89]
	v_mfma_f32_16x16x32_bf16 v[82:85], v[158:161], v[198:201], v[82:85]
	v_mfma_f32_16x16x32_bf16 v[78:81], v[130:133], v[206:209], v[78:81]
	v_mfma_f32_16x16x32_bf16 v[74:77], v[158:161], v[206:209], v[74:77]
	v_mfma_f32_16x16x32_bf16 v[70:73], v[130:133], v[214:217], v[70:73]
	v_mfma_f32_16x16x32_bf16 v[66:69], v[158:161], v[214:217], v[66:69]
	v_mfma_f32_16x16x32_bf16 v[94:97], v[134:137], v[194:197], v[94:97]
	v_mfma_f32_16x16x32_bf16 v[90:93], v[170:173], v[194:197], v[90:93]
	v_mfma_f32_16x16x32_bf16 v[86:89], v[134:137], v[202:205], v[86:89]
	v_mfma_f32_16x16x32_bf16 v[82:85], v[170:173], v[202:205], v[82:85]
	v_mfma_f32_16x16x32_bf16 v[78:81], v[134:137], v[210:213], v[78:81]
	v_mfma_f32_16x16x32_bf16 v[74:77], v[170:173], v[210:213], v[74:77]
	v_mfma_f32_16x16x32_bf16 v[70:73], v[134:137], v[218:221], v[70:73]
	v_mfma_f32_16x16x32_bf16 v[66:69], v[170:173], v[218:221], v[66:69]
	s_setprio 0
	s_setprio 1
	v_mfma_f32_16x16x32_bf16 v[30:33], v[174:177], v[190:193], v[30:33]
	v_mfma_f32_16x16x32_bf16 v[26:29], v[182:185], v[190:193], v[26:29]
	v_mfma_f32_16x16x32_bf16 v[22:25], v[174:177], v[198:201], v[22:25]
	v_mfma_f32_16x16x32_bf16 v[18:21], v[182:185], v[198:201], v[18:21]
	v_mfma_f32_16x16x32_bf16 v[14:17], v[174:177], v[206:209], v[14:17]
	v_mfma_f32_16x16x32_bf16 v[10:13], v[182:185], v[206:209], v[10:13]
	v_mfma_f32_16x16x32_bf16 v[6:9], v[174:177], v[214:217], v[6:9]
	v_mfma_f32_16x16x32_bf16 v[2:5], v[182:185], v[214:217], v[2:5]
	v_mfma_f32_16x16x32_bf16 v[30:33], v[178:181], v[194:197], v[30:33]
	v_mfma_f32_16x16x32_bf16 v[26:29], v[186:189], v[194:197], v[26:29]
	v_mfma_f32_16x16x32_bf16 v[22:25], v[178:181], v[202:205], v[22:25]
	v_mfma_f32_16x16x32_bf16 v[18:21], v[186:189], v[202:205], v[18:21]
	v_mfma_f32_16x16x32_bf16 v[14:17], v[178:181], v[210:213], v[14:17]
	v_mfma_f32_16x16x32_bf16 v[10:13], v[186:189], v[210:213], v[10:13]
	v_mfma_f32_16x16x32_bf16 v[6:9], v[178:181], v[218:221], v[6:9]
	v_mfma_f32_16x16x32_bf16 v[2:5], v[186:189], v[218:221], v[2:5]
	s_setprio 0
	s_barrier
	s_add_i32 s46, 0, 0x18000
	v_add_u32_e32 v155, s46, v165
	s_add_i32 s47, 0, 0x1c000
	ds_read_b128 v[130:133], v155
	ds_read_b128 v[134:137], v155 offset:1024
	ds_read_b128 v[158:161], v155 offset:2048
	ds_read_b128 v[170:173], v155 offset:3072
	v_add_u32_e32 v155, s47, v165
	ds_read_b128 v[174:177], v155
	ds_read_b128 v[178:181], v155 offset:1024
	ds_read_b128 v[182:185], v155 offset:2048
	ds_read_b128 v[186:189], v155 offset:3072
	v_lshl_add_u64 v[162:163], s[16:17], 0, v[140:141]
	s_mov_b32 m0, s27
	s_nop 0
	global_load_lds_dwordx4 v[162:163], off
	s_add_u32 s16, s16, 0x4000
	s_addc_u32 s17, s17, 0
	s_mov_b32 m0, s28
	v_lshl_add_u64 v[162:163], s[16:17], 0, v[144:145]
	ds_read_b128 v[190:193], v168 offset:32768
	ds_read_b128 v[194:197], v168 offset:33792
	ds_read_b128 v[198:201], v168 offset:34816
	ds_read_b128 v[202:205], v168 offset:35840
	ds_read_b128 v[206:209], v168 offset:36864
	ds_read_b128 v[210:213], v168 offset:37888
	ds_read_b128 v[214:217], v168 offset:38912
	ds_read_b128 v[218:221], v168 offset:39936
	global_load_lds_dwordx4 v[162:163], off
	v_lshl_add_u64 v[162:163], s[16:17], 0, v[140:141]
	s_mov_b32 m0, s29
	s_nop 0
	global_load_lds_dwordx4 v[162:163], off
	s_waitcnt vmcnt(8)
	s_waitcnt lgkmcnt(0)
	s_barrier
	s_setprio 1
	s_waitcnt lgkmcnt(0)
	v_mfma_f32_16x16x32_bf16 v[126:129], v[130:133], v[190:193], v[126:129]
	v_mfma_f32_16x16x32_bf16 v[122:125], v[158:161], v[190:193], v[122:125]
	v_mfma_f32_16x16x32_bf16 v[118:121], v[130:133], v[198:201], v[118:121]
	v_mfma_f32_16x16x32_bf16 v[114:117], v[158:161], v[198:201], v[114:117]
	v_mfma_f32_16x16x32_bf16 v[110:113], v[130:133], v[206:209], v[110:113]
	v_mfma_f32_16x16x32_bf16 v[106:109], v[158:161], v[206:209], v[106:109]
	v_mfma_f32_16x16x32_bf16 v[102:105], v[130:133], v[214:217], v[102:105]
	v_mfma_f32_16x16x32_bf16 v[98:101], v[158:161], v[214:217], v[98:101]
	v_mfma_f32_16x16x32_bf16 v[126:129], v[134:137], v[194:197], v[126:129]
	v_mfma_f32_16x16x32_bf16 v[122:125], v[170:173], v[194:197], v[122:125]
	v_mfma_f32_16x16x32_bf16 v[118:121], v[134:137], v[202:205], v[118:121]
	v_mfma_f32_16x16x32_bf16 v[114:117], v[170:173], v[202:205], v[114:117]
	v_mfma_f32_16x16x32_bf16 v[110:113], v[134:137], v[210:213], v[110:113]
	v_mfma_f32_16x16x32_bf16 v[106:109], v[170:173], v[210:213], v[106:109]
	v_mfma_f32_16x16x32_bf16 v[102:105], v[134:137], v[218:221], v[102:105]
	v_mfma_f32_16x16x32_bf16 v[98:101], v[170:173], v[218:221], v[98:101]
	s_setprio 0
	s_setprio 1
	v_mfma_f32_16x16x32_bf16 v[62:65], v[174:177], v[190:193], v[62:65]
	v_mfma_f32_16x16x32_bf16 v[58:61], v[182:185], v[190:193], v[58:61]
	v_mfma_f32_16x16x32_bf16 v[54:57], v[174:177], v[198:201], v[54:57]
	v_mfma_f32_16x16x32_bf16 v[50:53], v[182:185], v[198:201], v[50:53]
	v_mfma_f32_16x16x32_bf16 v[46:49], v[174:177], v[206:209], v[46:49]
	v_mfma_f32_16x16x32_bf16 v[42:45], v[182:185], v[206:209], v[42:45]
	v_mfma_f32_16x16x32_bf16 v[38:41], v[174:177], v[214:217], v[38:41]
	v_mfma_f32_16x16x32_bf16 v[34:37], v[182:185], v[214:217], v[34:37]
	v_mfma_f32_16x16x32_bf16 v[62:65], v[178:181], v[194:197], v[62:65]
	v_mfma_f32_16x16x32_bf16 v[58:61], v[186:189], v[194:197], v[58:61]
	v_mfma_f32_16x16x32_bf16 v[54:57], v[178:181], v[202:205], v[54:57]
	v_mfma_f32_16x16x32_bf16 v[50:53], v[186:189], v[202:205], v[50:53]
	v_mfma_f32_16x16x32_bf16 v[46:49], v[178:181], v[210:213], v[46:49]
	v_mfma_f32_16x16x32_bf16 v[42:45], v[186:189], v[210:213], v[42:45]
	v_mfma_f32_16x16x32_bf16 v[38:41], v[178:181], v[218:221], v[38:41]
	v_mfma_f32_16x16x32_bf16 v[34:37], v[186:189], v[218:221], v[34:37]
	s_setprio 0
	s_barrier
; #define PG8_STAGE(bufoff, gbase, voff) do { _Pragma("unroll") for (int _i = 0; _i < 2; ++_i) \
;         __builtin_amdgcn_global_load_lds((const unsigned*)((const char*)(gbase) + (voff)[_i]), (LAS unsigned*)(lds + (bufoff) + ldsw + _i * 8192), 16, 0, 0); } while (0)
; #define PG8_LDA(dst, b, h) do { _Pragma("unroll") for (int m = 0; m < 4; ++m) _Pragma("unroll") for (int k = 0; k < 2; ++k) dst[m][k] = *(const LAS bf16x8*)(lds + PG8_SA(b, h) + aoff + m * 2048 + k * 1024); } while (0)
; #define PG8_WAIT_V(n) asm volatile("s_waitcnt vmcnt(" #n ")" ::: "memory")
; #define PG8_WAIT_L(n) asm volatile("s_waitcnt lgkmcnt(" #n ")" ::: "memory")
; #define PG8_BAR __builtin_amdgcn_s_barrier()
; #define PG8_SCHED __builtin_amdgcn_sched_barrier(0)
; template <class Epi, class Sched, bool I8 = false>
; __device__ __forceinline__ void gemm_phase(LAS unsigned char* lds, const Gemm g, const Sched& S, const Epi& E) {
;     ...
;             PG8_LDA(At, 1, 1); PG8_STAGE(PG8_SB(1, 0), b3, voffB); PG8_STAGE(PG8_SB(1, 1), b3 + hstepB, voffB); PG8_STAGE(PG8_SA(1, 0), a3, voffA);
;             PG8_WAIT_V(8); PG8_WAIT_L(0); PG8_BAR; PG8_MMA(1, 0, At, B0); PG8_MMA(1, 1, At, B1); PG8_BAR; PG8_SCHED;
;         }
;         if (wr == 0) PG8_BAR;
	s_add_u32 s16, s14, 0x8000
	s_addc_u32 s17, s15, 0
	s_add_i32 s46, s46, s22
	v_lshl_add_u64 v[162:163], s[16:17], 0, v[142:143]
	s_mov_b32 m0, s46
	ds_read_b128 v[190:193], v168 offset:49152
	ds_read_b128 v[194:197], v168 offset:50176
	ds_read_b128 v[198:201], v168 offset:51200
	ds_read_b128 v[202:205], v168 offset:52224
	ds_read_b128 v[206:209], v168 offset:53248
	ds_read_b128 v[210:213], v168 offset:54272
	ds_read_b128 v[214:217], v168 offset:55296
	ds_read_b128 v[218:221], v168 offset:56320
	global_load_lds_dwordx4 v[162:163], off
	s_add_i32 m0, s46, 0x2000
	s_add_u32 s14, s14, 0xc000
	v_lshl_add_u64 v[162:163], s[16:17], 0, v[138:139]
	s_addc_u32 s15, s15, 0
	s_add_i32 s16, s47, s22
	global_load_lds_dwordx4 v[162:163], off
	v_lshl_add_u64 v[162:163], s[14:15], 0, v[142:143]
	s_mov_b32 m0, s16
	s_nop 0
	global_load_lds_dwordx4 v[162:163], off
	v_lshl_add_u64 v[162:163], s[14:15], 0, v[138:139]
	s_add_i32 m0, s16, 0x2000
	s_nop 0
	global_load_lds_dwordx4 v[162:163], off
	v_lshl_add_u64 v[162:163], s[12:13], 0, v[144:145]
	s_mov_b32 m0, s33
	s_nop 0
	global_load_lds_dwordx4 v[162:163], off
	s_waitcnt vmcnt(7)
	s_waitcnt lgkmcnt(0)
	s_barrier
	s_setprio 1
	s_waitcnt lgkmcnt(0)
	v_mfma_f32_16x16x32_bf16 v[94:97], v[130:133], v[190:193], v[94:97]
	v_mfma_f32_16x16x32_bf16 v[90:93], v[158:161], v[190:193], v[90:93]
	v_mfma_f32_16x16x32_bf16 v[86:89], v[130:133], v[198:201], v[86:89]
	v_mfma_f32_16x16x32_bf16 v[82:85], v[158:161], v[198:201], v[82:85]
	v_mfma_f32_16x16x32_bf16 v[78:81], v[130:133], v[206:209], v[78:81]
	v_mfma_f32_16x16x32_bf16 v[74:77], v[158:161], v[206:209], v[74:77]
	v_mfma_f32_16x16x32_bf16 v[70:73], v[130:133], v[214:217], v[70:73]
	v_mfma_f32_16x16x32_bf16 v[66:69], v[158:161], v[214:217], v[66:69]
	v_mfma_f32_16x16x32_bf16 v[94:97], v[134:137], v[194:197], v[94:97]
	v_mfma_f32_16x16x32_bf16 v[90:93], v[170:173], v[194:197], v[90:93]
	v_mfma_f32_16x16x32_bf16 v[86:89], v[134:137], v[202:205], v[86:89]
	v_mfma_f32_16x16x32_bf16 v[82:85], v[170:173], v[202:205], v[82:85]
	v_mfma_f32_16x16x32_bf16 v[78:81], v[134:137], v[210:213], v[78:81]
	v_mfma_f32_16x16x32_bf16 v[74:77], v[170:173], v[210:213], v[74:77]
	v_mfma_f32_16x16x32_bf16 v[70:73], v[134:137], v[218:221], v[70:73]
	v_mfma_f32_16x16x32_bf16 v[66:69], v[170:173], v[218:221], v[66:69]
	s_setprio 0
	s_setprio 1
	v_mfma_f32_16x16x32_bf16 v[30:33], v[174:177], v[190:193], v[30:33]
	v_mfma_f32_16x16x32_bf16 v[26:29], v[182:185], v[190:193], v[26:29]
	v_mfma_f32_16x16x32_bf16 v[22:25], v[174:177], v[198:201], v[22:25]
	v_mfma_f32_16x16x32_bf16 v[18:21], v[182:185], v[198:201], v[18:21]
	v_mfma_f32_16x16x32_bf16 v[14:17], v[174:177], v[206:209], v[14:17]
	v_mfma_f32_16x16x32_bf16 v[10:13], v[182:185], v[206:209], v[10:13]
	v_mfma_f32_16x16x32_bf16 v[6:9], v[174:177], v[214:217], v[6:9]
	v_mfma_f32_16x16x32_bf16 v[2:5], v[182:185], v[214:217], v[2:5]
	v_mfma_f32_16x16x32_bf16 v[30:33], v[178:181], v[194:197], v[30:33]
	v_mfma_f32_16x16x32_bf16 v[26:29], v[186:189], v[194:197], v[26:29]
	v_mfma_f32_16x16x32_bf16 v[22:25], v[178:181], v[202:205], v[22:25]
	v_mfma_f32_16x16x32_bf16 v[18:21], v[186:189], v[202:205], v[18:21]
	v_mfma_f32_16x16x32_bf16 v[14:17], v[178:181], v[210:213], v[14:17]
	v_mfma_f32_16x16x32_bf16 v[10:13], v[186:189], v[210:213], v[10:13]
	v_mfma_f32_16x16x32_bf16 v[6:9], v[178:181], v[218:221], v[6:9]
	v_mfma_f32_16x16x32_bf16 v[2:5], v[186:189], v[218:221], v[2:5]
	s_setprio 0
	s_barrier
	s_add_i32 s45, s45, 2
	s_add_u32 s10, s10, 0x10000
	s_addc_u32 s11, s11, 0
	s_add_u32 s43, s43, 0x10000
	s_addc_u32 s44, s44, 0
	s_cmp_gt_u32 s45, 5
	s_cbranch_scc0 .LBB0_2685
	s_and_b64 vcc, exec, s[6:7]
	s_cbranch_vccz .LBB0_2688
	s_barrier

; #define PG8_STAGE(bufoff, gbase, voff) do { _Pragma("unroll") for (int _i = 0; _i < 2; ++_i) \
;         __builtin_amdgcn_global_load_lds((const unsigned*)((const char*)(gbase) + (voff)[_i]), (LAS unsigned*)(lds + (bufoff) + ldsw + _i * 8192), 16, 0, 0); } while (0)
; #define PG8_LDA(dst, b, h) do { _Pragma("unroll") for (int m = 0; m < 4; ++m) _Pragma("unroll") for (int k = 0; k < 2; ++k) dst[m][k] = *(const LAS bf16x8*)(lds + PG8_SA(b, h) + aoff + m * 2048 + k * 1024); } while (0)
; #define PG8_LDB(dst, b, h) do { _Pragma("unroll") for (int n = 0; n < 2; ++n) _Pragma("unroll") for (int k = 0; k < 2; ++k) dst[n][k] = *(const LAS bf16x8*)(lds + PG8_SB(b, h) + boff + n * 2048 + k * 1024); } while (0)
; #define PG8_WAIT_V(n) asm volatile("s_waitcnt vmcnt(" #n ")" ::: "memory")
; #define PG8_WAIT_L(n) asm volatile("s_waitcnt lgkmcnt(" #n ")" ::: "memory")
; #define PG8_BAR __builtin_amdgcn_s_barrier()
; #define PG8_SCHED __builtin_amdgcn_sched_barrier(0)
; template <class Epi, class Sched, bool I8 = false>
; __device__ __forceinline__ void gemm_phase(LAS unsigned char* lds, const Gemm g, const Sched& S, const Epi& E) {
;     ...
;             const char* a1 = cA + (size_t)(t + 1) * kstep;
;             const char* a2 = last ? nA : cA + (size_t)(t + 2) * kstep; const char* b2 = last ? nB : cB + (size_t)(t + 2) * kstep;
;             const char* a3 = a2 + kstep; const char* b3 = b2 + kstep;
;             PG8_LDB(B0, 0, 0); PG8_LDB(B1, 0, 1); PG8_SCHED; PG8_LDA(At, 0, 0); PG8_STAGE(PG8_SA(1, 1), a1 + hstepA, voffA);
;             PG8_WAIT_V(8); PG8_WAIT_L(0); PG8_BAR; PG8_MMA(0, 0, At, B0); PG8_MMA(0, 1, At, B1); PG8_BAR; PG8_SCHED;
;             PG8_LDA(At, 0, 1); PG8_STAGE(PG8_SB(0, 0), b2, voffB); PG8_STAGE(PG8_SB(0, 1), b2 + hstepB, voffB); PG8_STAGE(PG8_SA(0, 0), a2, voffA);
;             PG8_WAIT_V(8); PG8_WAIT_L(0); PG8_BAR; PG8_MMA(1, 0, At, B0); PG8_MMA(1, 1, At, B1); PG8_BAR; PG8_SCHED;
.LBB0_3744:
	ds_read_b128 v[130:133], v231
	ds_read_b128 v[134:137], v231 offset:1024
	ds_read_b128 v[138:141], v231 offset:2048
	ds_read_b128 v[142:145], v231 offset:3072
	ds_read_b128 v[146:149], v232
	ds_read_b128 v[150:153], v232 offset:1024
	ds_read_b128 v[154:157], v232 offset:2048
	ds_read_b128 v[158:161], v232 offset:3072
	s_add_u32 s34, s30, 0x4000
	s_addc_u32 s35, s31, 0
	s_cmp_eq_u32 s59, 60
	s_cselect_b32 s38, s23, s34
	s_cselect_b32 s39, s5, s35
	s_cselect_b32 s36, s29, s57
	s_cselect_b32 s37, s21, s58
	s_add_u32 s34, s38, 0x8000
	s_addc_u32 s35, s39, 0
	s_sub_u32 s98, s30, 0x4000
	s_subb_u32 s99, s31, 0
	v_lshl_add_u64 v[212:213], s[98:99], 0, v[198:199]
	s_mov_b32 m0, s52
	s_nop 0
	global_load_lds_dwordx4 v[212:213], off
	v_lshl_add_u64 v[212:213], s[30:31], 0, v[204:205]
	s_add_i32 m0, s44, 0xc000
	ds_read_b128 v[162:165], v233
	ds_read_b128 v[166:169], v233 offset:1024
	ds_read_b128 v[170:173], v233 offset:2048
	ds_read_b128 v[174:177], v233 offset:3072
	ds_read_b128 v[178:181], v233 offset:4096
	ds_read_b128 v[182:185], v233 offset:5120
	ds_read_b128 v[186:189], v233 offset:6144
	ds_read_b128 v[190:193], v233 offset:7168
	global_load_lds_dwordx4 v[212:213], off
	v_lshl_add_u64 v[212:213], s[30:31], 0, v[206:207]
	s_add_i32 m0, s44, 0xe000
	s_nop 0
	global_load_lds_dwordx4 v[212:213], off
	s_waitcnt vmcnt(8)
	s_waitcnt lgkmcnt(0)
	s_barrier
	s_setprio 1
	s_waitcnt lgkmcnt(0)
	v_mfma_f32_16x16x32_bf16 v[126:129], v[130:133], v[162:165], v[126:129]
	v_mfma_f32_16x16x32_bf16 v[122:125], v[138:141], v[162:165], v[122:125]
	v_mfma_f32_16x16x32_bf16 v[118:121], v[130:133], v[170:173], v[118:121]
	v_mfma_f32_16x16x32_bf16 v[110:113], v[138:141], v[170:173], v[110:113]
	v_mfma_f32_16x16x32_bf16 v[102:105], v[130:133], v[178:181], v[102:105]
	v_mfma_f32_16x16x32_bf16 v[94:97], v[138:141], v[178:181], v[94:97]
	v_mfma_f32_16x16x32_bf16 v[86:89], v[130:133], v[186:189], v[86:89]
	v_mfma_f32_16x16x32_bf16 v[78:81], v[138:141], v[186:189], v[78:81]
	v_mfma_f32_16x16x32_bf16 v[126:129], v[134:137], v[166:169], v[126:129]
	v_mfma_f32_16x16x32_bf16 v[122:125], v[142:145], v[166:169], v[122:125]
	v_mfma_f32_16x16x32_bf16 v[118:121], v[134:137], v[174:177], v[118:121]
	v_mfma_f32_16x16x32_bf16 v[110:113], v[142:145], v[174:177], v[110:113]
	v_mfma_f32_16x16x32_bf16 v[102:105], v[134:137], v[182:185], v[102:105]
	v_mfma_f32_16x16x32_bf16 v[94:97], v[142:145], v[182:185], v[94:97]
	v_mfma_f32_16x16x32_bf16 v[86:89], v[134:137], v[190:193], v[86:89]
	v_mfma_f32_16x16x32_bf16 v[78:81], v[142:145], v[190:193], v[78:81]
	s_setprio 0
	s_setprio 1
	v_mfma_f32_16x16x32_bf16 v[114:117], v[146:149], v[162:165], v[114:117]
	v_mfma_f32_16x16x32_bf16 v[106:109], v[154:157], v[162:165], v[106:109]
	v_mfma_f32_16x16x32_bf16 v[98:101], v[146:149], v[170:173], v[98:101]
	v_mfma_f32_16x16x32_bf16 v[90:93], v[154:157], v[170:173], v[90:93]
	v_mfma_f32_16x16x32_bf16 v[82:85], v[146:149], v[178:181], v[82:85]
	v_mfma_f32_16x16x32_bf16 v[74:77], v[154:157], v[178:181], v[74:77]
	v_mfma_f32_16x16x32_bf16 v[70:73], v[146:149], v[186:189], v[70:73]
	v_mfma_f32_16x16x32_bf16 v[66:69], v[154:157], v[186:189], v[66:69]
	v_mfma_f32_16x16x32_bf16 v[114:117], v[150:153], v[166:169], v[114:117]
	v_mfma_f32_16x16x32_bf16 v[106:109], v[158:161], v[166:169], v[106:109]
	v_mfma_f32_16x16x32_bf16 v[98:101], v[150:153], v[174:177], v[98:101]
	v_mfma_f32_16x16x32_bf16 v[90:93], v[158:161], v[174:177], v[90:93]
	v_mfma_f32_16x16x32_bf16 v[82:85], v[150:153], v[182:185], v[82:85]
	v_mfma_f32_16x16x32_bf16 v[74:77], v[158:161], v[182:185], v[74:77]
	v_mfma_f32_16x16x32_bf16 v[70:73], v[150:153], v[190:193], v[70:73]
	v_mfma_f32_16x16x32_bf16 v[66:69], v[158:161], v[190:193], v[66:69]
	s_setprio 0
	s_barrier
	s_add_i32 s60, s55, s43
	v_lshl_add_u64 v[212:213], s[36:37], 0, v[196:197]
	s_mov_b32 m0, s60
	ds_read_b128 v[162:165], v233 offset:16384
	ds_read_b128 v[166:169], v233 offset:17408
	ds_read_b128 v[170:173], v233 offset:18432
	ds_read_b128 v[174:177], v233 offset:19456
	ds_read_b128 v[178:181], v233 offset:20480
	ds_read_b128 v[182:185], v233 offset:21504
	ds_read_b128 v[186:189], v233 offset:22528
	ds_read_b128 v[190:193], v233 offset:23552
	global_load_lds_dwordx4 v[212:213], off
	s_add_i32 m0, s60, 0x2000
	s_add_u32 s60, s36, 0x4000
	v_lshl_add_u64 v[212:213], s[36:37], 0, v[200:201]
	s_addc_u32 s61, s37, 0
	s_add_i32 s62, s56, s43
	global_load_lds_dwordx4 v[212:213], off
	v_lshl_add_u64 v[212:213], s[60:61], 0, v[196:197]
	s_mov_b32 m0, s62
	s_nop 0
	global_load_lds_dwordx4 v[212:213], off
	v_lshl_add_u64 v[212:213], s[60:61], 0, v[200:201]
	s_add_i32 m0, s62, 0x2000
	s_nop 0
	global_load_lds_dwordx4 v[212:213], off
	v_lshl_add_u64 v[212:213], s[38:39], 0, v[194:195]
	s_mov_b32 m0, s44
	s_nop 0
	global_load_lds_dwordx4 v[212:213], off
	s_waitcnt vmcnt(7)
	s_waitcnt lgkmcnt(0)
	s_barrier
; #define PG8_STAGE(bufoff, gbase, voff) do { _Pragma("unroll") for (int _i = 0; _i < 2; ++_i) \
;         __builtin_amdgcn_global_load_lds((const unsigned*)((const char*)(gbase) + (voff)[_i]), (LAS unsigned*)(lds + (bufoff) + ldsw + _i * 8192), 16, 0, 0); } while (0)
; #define PG8_LDA(dst, b, h) do { _Pragma("unroll") for (int m = 0; m < 4; ++m) _Pragma("unroll") for (int k = 0; k < 2; ++k) dst[m][k] = *(const LAS bf16x8*)(lds + PG8_SA(b, h) + aoff + m * 2048 + k * 1024); } while (0)
; #define PG8_LDB(dst, b, h) do { _Pragma("unroll") for (int n = 0; n < 2; ++n) _Pragma("unroll") for (int k = 0; k < 2; ++k) dst[n][k] = *(const LAS bf16x8*)(lds + PG8_SB(b, h) + boff + n * 2048 + k * 1024); } while (0)
; #define PG8_WAIT_V(n) asm volatile("s_waitcnt vmcnt(" #n ")" ::: "memory")
; #define PG8_WAIT_L(n) asm volatile("s_waitcnt lgkmcnt(" #n ")" ::: "memory")
; #define PG8_BAR __builtin_amdgcn_s_barrier()
; #define PG8_SCHED __builtin_amdgcn_sched_barrier(0)
; template <class Epi, class Sched, bool I8 = false>
; __device__ __forceinline__ void gemm_phase(LAS unsigned char* lds, const Gemm g, const Sched& S, const Epi& E) {
;     ...
;             PG8_WAIT_V(8); PG8_WAIT_L(0); PG8_BAR; PG8_MMA(1, 0, At, B0); PG8_MMA(1, 1, At, B1); PG8_BAR; PG8_SCHED;
;             PG8_LDB(B0, 1, 0); PG8_LDB(B1, 1, 1); PG8_SCHED; PG8_LDA(At, 1, 0); PG8_STAGE(PG8_SA(0, 1), a2 + hstepA, voffA);
;             PG8_WAIT_V(8); PG8_WAIT_L(0); PG8_BAR; PG8_MMA(0, 0, At, B0); PG8_MMA(0, 1, At, B1); PG8_BAR; PG8_SCHED;
	s_setprio 1
	s_waitcnt lgkmcnt(0)
	v_mfma_f32_16x16x32_bf16 v[62:65], v[130:133], v[162:165], v[62:65]
	v_mfma_f32_16x16x32_bf16 v[58:61], v[138:141], v[162:165], v[58:61]
	v_mfma_f32_16x16x32_bf16 v[54:57], v[130:133], v[170:173], v[54:57]
	v_mfma_f32_16x16x32_bf16 v[46:49], v[138:141], v[170:173], v[46:49]
	v_mfma_f32_16x16x32_bf16 v[38:41], v[130:133], v[178:181], v[38:41]
	v_mfma_f32_16x16x32_bf16 v[30:33], v[138:141], v[178:181], v[30:33]
	v_mfma_f32_16x16x32_bf16 v[22:25], v[130:133], v[186:189], v[22:25]
	v_mfma_f32_16x16x32_bf16 v[14:17], v[138:141], v[186:189], v[14:17]
	v_mfma_f32_16x16x32_bf16 v[62:65], v[134:137], v[166:169], v[62:65]
	v_mfma_f32_16x16x32_bf16 v[58:61], v[142:145], v[166:169], v[58:61]
	v_mfma_f32_16x16x32_bf16 v[54:57], v[134:137], v[174:177], v[54:57]
	v_mfma_f32_16x16x32_bf16 v[46:49], v[142:145], v[174:177], v[46:49]
	v_mfma_f32_16x16x32_bf16 v[38:41], v[134:137], v[182:185], v[38:41]
	v_mfma_f32_16x16x32_bf16 v[30:33], v[142:145], v[182:185], v[30:33]
	v_mfma_f32_16x16x32_bf16 v[22:25], v[134:137], v[190:193], v[22:25]
	v_mfma_f32_16x16x32_bf16 v[14:17], v[142:145], v[190:193], v[14:17]
	s_setprio 0
	s_setprio 1
	v_mfma_f32_16x16x32_bf16 v[50:53], v[146:149], v[162:165], v[50:53]
	v_mfma_f32_16x16x32_bf16 v[42:45], v[154:157], v[162:165], v[42:45]
	v_mfma_f32_16x16x32_bf16 v[34:37], v[146:149], v[170:173], v[34:37]
	v_mfma_f32_16x16x32_bf16 v[26:29], v[154:157], v[170:173], v[26:29]
	v_mfma_f32_16x16x32_bf16 v[18:21], v[146:149], v[178:181], v[18:21]
	v_mfma_f32_16x16x32_bf16 v[10:13], v[154:157], v[178:181], v[10:13]
	v_mfma_f32_16x16x32_bf16 v[6:9], v[146:149], v[186:189], v[6:9]
	v_mfma_f32_16x16x32_bf16 v[2:5], v[154:157], v[186:189], v[2:5]
	v_mfma_f32_16x16x32_bf16 v[50:53], v[150:153], v[166:169], v[50:53]
	v_mfma_f32_16x16x32_bf16 v[42:45], v[158:161], v[166:169], v[42:45]
	v_mfma_f32_16x16x32_bf16 v[34:37], v[150:153], v[174:177], v[34:37]
	v_mfma_f32_16x16x32_bf16 v[26:29], v[158:161], v[174:177], v[26:29]
	v_mfma_f32_16x16x32_bf16 v[18:21], v[150:153], v[182:185], v[18:21]
	v_mfma_f32_16x16x32_bf16 v[10:13], v[158:161], v[182:185], v[10:13]
	v_mfma_f32_16x16x32_bf16 v[6:9], v[150:153], v[190:193], v[6:9]
	v_mfma_f32_16x16x32_bf16 v[2:5], v[158:161], v[190:193], v[2:5]
	s_setprio 0
	s_barrier
	s_add_i32 s60, 0, 0x18000
	s_add_i32 s61, 0, 0x1c000
	v_add_u32_e32 v142, s60, v230
	v_add_u32_e32 v158, s61, v230
	ds_read_b128 v[130:133], v142
	ds_read_b128 v[134:137], v142 offset:1024
	ds_read_b128 v[138:141], v142 offset:2048
	ds_read_b128 v[142:145], v142 offset:3072
	ds_read_b128 v[146:149], v158
	ds_read_b128 v[150:153], v158 offset:1024
	ds_read_b128 v[154:157], v158 offset:2048
	ds_read_b128 v[158:161], v158 offset:3072
	v_lshl_add_u64 v[212:213], s[38:39], 0, v[198:199]
	s_mov_b32 m0, s45
	s_nop 0
	global_load_lds_dwordx4 v[212:213], off
	s_add_u32 s38, s38, 0x4000
	s_addc_u32 s39, s39, 0
	s_mov_b32 m0, s46
	v_lshl_add_u64 v[212:213], s[38:39], 0, v[194:195]
	ds_read_b128 v[162:165], v233 offset:32768
	ds_read_b128 v[166:169], v233 offset:33792
	ds_read_b128 v[170:173], v233 offset:34816
	ds_read_b128 v[174:177], v233 offset:35840
	ds_read_b128 v[178:181], v233 offset:36864
	ds_read_b128 v[182:185], v233 offset:37888
	ds_read_b128 v[186:189], v233 offset:38912
	ds_read_b128 v[190:193], v233 offset:39936
	global_load_lds_dwordx4 v[212:213], off
	v_lshl_add_u64 v[212:213], s[38:39], 0, v[198:199]
	s_mov_b32 m0, s47
	s_nop 0
	global_load_lds_dwordx4 v[212:213], off
	s_waitcnt vmcnt(8)
	s_waitcnt lgkmcnt(0)
	s_barrier
	s_setprio 1
	s_waitcnt lgkmcnt(0)
	v_mfma_f32_16x16x32_bf16 v[126:129], v[130:133], v[162:165], v[126:129]
	v_mfma_f32_16x16x32_bf16 v[122:125], v[138:141], v[162:165], v[122:125]
	v_mfma_f32_16x16x32_bf16 v[118:121], v[130:133], v[170:173], v[118:121]
	v_mfma_f32_16x16x32_bf16 v[110:113], v[138:141], v[170:173], v[110:113]
	v_mfma_f32_16x16x32_bf16 v[102:105], v[130:133], v[178:181], v[102:105]
	v_mfma_f32_16x16x32_bf16 v[94:97], v[138:141], v[178:181], v[94:97]
	v_mfma_f32_16x16x32_bf16 v[86:89], v[130:133], v[186:189], v[86:89]
	v_mfma_f32_16x16x32_bf16 v[78:81], v[138:141], v[186:189], v[78:81]
	v_mfma_f32_16x16x32_bf16 v[126:129], v[134:137], v[166:169], v[126:129]
	v_mfma_f32_16x16x32_bf16 v[122:125], v[142:145], v[166:169], v[122:125]
	v_mfma_f32_16x16x32_bf16 v[118:121], v[134:137], v[174:177], v[118:121]
	v_mfma_f32_16x16x32_bf16 v[110:113], v[142:145], v[174:177], v[110:113]
	v_mfma_f32_16x16x32_bf16 v[102:105], v[134:137], v[182:185], v[102:105]
	v_mfma_f32_16x16x32_bf16 v[94:97], v[142:145], v[182:185], v[94:97]
	v_mfma_f32_16x16x32_bf16 v[86:89], v[134:137], v[190:193], v[86:89]
	v_mfma_f32_16x16x32_bf16 v[78:81], v[142:145], v[190:193], v[78:81]
	s_setprio 0
	s_setprio 1
	v_mfma_f32_16x16x32_bf16 v[114:117], v[146:149], v[162:165], v[114:117]
	v_mfma_f32_16x16x32_bf16 v[106:109], v[154:157], v[162:165], v[106:109]
	v_mfma_f32_16x16x32_bf16 v[98:101], v[146:149], v[170:173], v[98:101]
	v_mfma_f32_16x16x32_bf16 v[90:93], v[154:157], v[170:173], v[90:93]
	v_mfma_f32_16x16x32_bf16 v[82:85], v[146:149], v[178:181], v[82:85]
	v_mfma_f32_16x16x32_bf16 v[74:77], v[154:157], v[178:181], v[74:77]
	v_mfma_f32_16x16x32_bf16 v[70:73], v[146:149], v[186:189], v[70:73]
	v_mfma_f32_16x16x32_bf16 v[66:69], v[154:157], v[186:189], v[66:69]
	v_mfma_f32_16x16x32_bf16 v[114:117], v[150:153], v[166:169], v[114:117]
	v_mfma_f32_16x16x32_bf16 v[106:109], v[158:161], v[166:169], v[106:109]
	v_mfma_f32_16x16x32_bf16 v[98:101], v[150:153], v[174:177], v[98:101]
	v_mfma_f32_16x16x32_bf16 v[90:93], v[158:161], v[174:177], v[90:93]
	v_mfma_f32_16x16x32_bf16 v[82:85], v[150:153], v[182:185], v[82:85]
	v_mfma_f32_16x16x32_bf16 v[74:77], v[158:161], v[182:185], v[74:77]
	v_mfma_f32_16x16x32_bf16 v[70:73], v[150:153], v[190:193], v[70:73]
	v_mfma_f32_16x16x32_bf16 v[66:69], v[158:161], v[190:193], v[66:69]
	s_setprio 0
	s_barrier
; #define PG8_STAGE(bufoff, gbase, voff) do { _Pragma("unroll") for (int _i = 0; _i < 2; ++_i) \
;         __builtin_amdgcn_global_load_lds((const unsigned*)((const char*)(gbase) + (voff)[_i]), (LAS unsigned*)(lds + (bufoff) + ldsw + _i * 8192), 16, 0, 0); } while (0)
; #define PG8_LDA(dst, b, h) do { _Pragma("unroll") for (int m = 0; m < 4; ++m) _Pragma("unroll") for (int k = 0; k < 2; ++k) dst[m][k] = *(const LAS bf16x8*)(lds + PG8_SA(b, h) + aoff + m * 2048 + k * 1024); } while (0)
; #define PG8_WAIT_V(n) asm volatile("s_waitcnt vmcnt(" #n ")" ::: "memory")
; #define PG8_WAIT_L(n) asm volatile("s_waitcnt lgkmcnt(" #n ")" ::: "memory")
; #define PG8_BAR __builtin_amdgcn_s_barrier()
; #define PG8_SCHED __builtin_amdgcn_sched_barrier(0)
; template <class Epi, class Sched, bool I8 = false>
; __device__ __forceinline__ void gemm_phase(LAS unsigned char* lds, const Gemm g, const Sched& S, const Epi& E) {
;     ...
;             PG8_LDA(At, 1, 1); PG8_STAGE(PG8_SB(1, 0), b3, voffB); PG8_STAGE(PG8_SB(1, 1), b3 + hstepB, voffB); PG8_STAGE(PG8_SA(1, 0), a3, voffA);
;             PG8_WAIT_V(8); PG8_WAIT_L(0); PG8_BAR; PG8_MMA(1, 0, At, B0); PG8_MMA(1, 1, At, B1); PG8_BAR; PG8_SCHED;
;         }
;         if (wr == 0) PG8_BAR;
	s_add_u32 s38, s36, 0x8000
	s_addc_u32 s39, s37, 0
	s_add_i32 s60, s60, s43
	v_lshl_add_u64 v[212:213], s[38:39], 0, v[196:197]
	s_mov_b32 m0, s60
	ds_read_b128 v[162:165], v233 offset:49152
	ds_read_b128 v[166:169], v233 offset:50176
	ds_read_b128 v[170:173], v233 offset:51200
	ds_read_b128 v[174:177], v233 offset:52224
	ds_read_b128 v[178:181], v233 offset:53248
	ds_read_b128 v[182:185], v233 offset:54272
	ds_read_b128 v[186:189], v233 offset:55296
	ds_read_b128 v[190:193], v233 offset:56320
	global_load_lds_dwordx4 v[212:213], off
	s_add_i32 m0, s60, 0x2000
	s_add_u32 s36, s36, 0xc000
	v_lshl_add_u64 v[212:213], s[38:39], 0, v[200:201]
	s_addc_u32 s37, s37, 0
	s_add_i32 s38, s61, s43
	global_load_lds_dwordx4 v[212:213], off
	v_lshl_add_u64 v[212:213], s[36:37], 0, v[196:197]
	s_mov_b32 m0, s38
	s_nop 0
	global_load_lds_dwordx4 v[212:213], off
	v_lshl_add_u64 v[212:213], s[36:37], 0, v[200:201]
	s_add_i32 m0, s38, 0x2000
	s_nop 0
	global_load_lds_dwordx4 v[212:213], off
	v_lshl_add_u64 v[212:213], s[34:35], 0, v[194:195]
	s_mov_b32 m0, s51
	s_nop 0
	global_load_lds_dwordx4 v[212:213], off
	s_waitcnt vmcnt(7)
	s_waitcnt lgkmcnt(0)
	s_barrier
	s_setprio 1
	s_waitcnt lgkmcnt(0)
	v_mfma_f32_16x16x32_bf16 v[62:65], v[130:133], v[162:165], v[62:65]
	v_mfma_f32_16x16x32_bf16 v[58:61], v[138:141], v[162:165], v[58:61]
	v_mfma_f32_16x16x32_bf16 v[54:57], v[130:133], v[170:173], v[54:57]
	v_mfma_f32_16x16x32_bf16 v[46:49], v[138:141], v[170:173], v[46:49]
	v_mfma_f32_16x16x32_bf16 v[38:41], v[130:133], v[178:181], v[38:41]
	v_mfma_f32_16x16x32_bf16 v[30:33], v[138:141], v[178:181], v[30:33]
	v_mfma_f32_16x16x32_bf16 v[22:25], v[130:133], v[186:189], v[22:25]
	v_mfma_f32_16x16x32_bf16 v[14:17], v[138:141], v[186:189], v[14:17]
	v_mfma_f32_16x16x32_bf16 v[62:65], v[134:137], v[166:169], v[62:65]
	v_mfma_f32_16x16x32_bf16 v[58:61], v[142:145], v[166:169], v[58:61]
	v_mfma_f32_16x16x32_bf16 v[54:57], v[134:137], v[174:177], v[54:57]
	v_mfma_f32_16x16x32_bf16 v[46:49], v[142:145], v[174:177], v[46:49]
	v_mfma_f32_16x16x32_bf16 v[38:41], v[134:137], v[182:185], v[38:41]
	v_mfma_f32_16x16x32_bf16 v[30:33], v[142:145], v[182:185], v[30:33]
	v_mfma_f32_16x16x32_bf16 v[22:25], v[134:137], v[190:193], v[22:25]
	v_mfma_f32_16x16x32_bf16 v[14:17], v[142:145], v[190:193], v[14:17]
	s_setprio 0
	s_setprio 1
	v_mfma_f32_16x16x32_bf16 v[50:53], v[146:149], v[162:165], v[50:53]
	v_mfma_f32_16x16x32_bf16 v[42:45], v[154:157], v[162:165], v[42:45]
	v_mfma_f32_16x16x32_bf16 v[34:37], v[146:149], v[170:173], v[34:37]
	v_mfma_f32_16x16x32_bf16 v[26:29], v[154:157], v[170:173], v[26:29]
	v_mfma_f32_16x16x32_bf16 v[18:21], v[146:149], v[178:181], v[18:21]
	v_mfma_f32_16x16x32_bf16 v[10:13], v[154:157], v[178:181], v[10:13]
	v_mfma_f32_16x16x32_bf16 v[6:9], v[146:149], v[186:189], v[6:9]
	v_mfma_f32_16x16x32_bf16 v[2:5], v[154:157], v[186:189], v[2:5]
	v_mfma_f32_16x16x32_bf16 v[50:53], v[150:153], v[166:169], v[50:53]
	v_mfma_f32_16x16x32_bf16 v[42:45], v[158:161], v[166:169], v[42:45]
	v_mfma_f32_16x16x32_bf16 v[34:37], v[150:153], v[174:177], v[34:37]
	v_mfma_f32_16x16x32_bf16 v[26:29], v[158:161], v[174:177], v[26:29]
	v_mfma_f32_16x16x32_bf16 v[18:21], v[150:153], v[182:185], v[18:21]
	v_mfma_f32_16x16x32_bf16 v[10:13], v[158:161], v[182:185], v[10:13]
	v_mfma_f32_16x16x32_bf16 v[6:9], v[150:153], v[190:193], v[6:9]
	v_mfma_f32_16x16x32_bf16 v[2:5], v[158:161], v[190:193], v[2:5]
	s_setprio 0
	s_barrier
	s_add_i32 s59, s59, 2
	s_add_u32 s30, s30, 0x10000
	s_addc_u32 s31, s31, 0
	s_add_u32 s57, s57, 0x10000
	s_addc_u32 s58, s58, 0
	s_cmp_gt_u32 s59, 61
	s_cbranch_scc0 .LBB0_3744
	s_and_b64 vcc, exec, s[6:7]
	s_cbranch_vccz .LBB0_3747
	s_barrier

; #define PG8_STAGE(bufoff, gbase, voff) do { _Pragma("unroll") for (int _i = 0; _i < 2; ++_i) \
;         __builtin_amdgcn_global_load_lds((const unsigned*)((const char*)(gbase) + (voff)[_i]), (LAS unsigned*)(lds + (bufoff) + ldsw + _i * 8192), 16, 0, 0); } while (0)
; #define PG8_LDA(dst, b, h) do { _Pragma("unroll") for (int m = 0; m < 4; ++m) _Pragma("unroll") for (int k = 0; k < 2; ++k) dst[m][k] = *(const LAS bf16x8*)(lds + PG8_SA(b, h) + aoff + m * 2048 + k * 1024); } while (0)
; #define PG8_LDB(dst, b, h) do { _Pragma("unroll") for (int n = 0; n < 2; ++n) _Pragma("unroll") for (int k = 0; k < 2; ++k) dst[n][k] = *(const LAS bf16x8*)(lds + PG8_SB(b, h) + boff + n * 2048 + k * 1024); } while (0)
; #define PG8_WAIT_V(n) asm volatile("s_waitcnt vmcnt(" #n ")" ::: "memory")
; #define PG8_WAIT_L(n) asm volatile("s_waitcnt lgkmcnt(" #n ")" ::: "memory")
; #define PG8_BAR __builtin_amdgcn_s_barrier()
; #define PG8_SCHED __builtin_amdgcn_sched_barrier(0)
; template <class Epi, class Sched, bool I8 = false>
; __device__ __forceinline__ void gemm_phase(LAS unsigned char* lds, const Gemm g, const Sched& S, const Epi& E) {
;     ...
;             const char* a1 = cA + (size_t)(t + 1) * kstep;
;             const char* a2 = last ? nA : cA + (size_t)(t + 2) * kstep; const char* b2 = last ? nB : cB + (size_t)(t + 2) * kstep;
;             const char* a3 = a2 + kstep; const char* b3 = b2 + kstep;
;             PG8_LDB(B0, 0, 0); PG8_LDB(B1, 0, 1); PG8_SCHED; PG8_LDA(At, 0, 0); PG8_STAGE(PG8_SA(1, 1), a1 + hstepA, voffA);
;             PG8_WAIT_V(8); PG8_WAIT_L(0); PG8_BAR; PG8_MMA(0, 0, At, B0); PG8_MMA(0, 1, At, B1); PG8_BAR; PG8_SCHED;
;             PG8_LDA(At, 0, 1); PG8_STAGE(PG8_SB(0, 0), b2, voffB); PG8_STAGE(PG8_SB(0, 1), b2 + hstepB, voffB); PG8_STAGE(PG8_SA(0, 0), a2, voffA);
;             PG8_WAIT_V(8); PG8_WAIT_L(0); PG8_BAR; PG8_MMA(1, 0, At, B0); PG8_MMA(1, 1, At, B1); PG8_BAR; PG8_SCHED;
.LBB0_4168:
	ds_read_b128 v[66:69], v178
	ds_read_b128 v[70:73], v178 offset:1024
	ds_read_b128 v[74:77], v178 offset:2048
	ds_read_b128 v[78:81], v178 offset:3072
	ds_read_b128 v[146:149], v179
	ds_read_b128 v[150:153], v179 offset:1024
	ds_read_b128 v[172:175], v179 offset:2048
	ds_read_b128 v[182:185], v179 offset:3072
	s_add_u32 s22, s20, 0x4000
	s_addc_u32 s23, s21, 0
	s_cmpk_eq_i32 s51, 0x52
	s_cselect_b32 s26, s0, s22
	s_cselect_b32 s27, s1, s23
	s_cselect_b32 s24, s18, s49
	s_cselect_b32 s25, s19, s50
	s_add_u32 s22, s26, 0x8000
	s_addc_u32 s23, s27, 0
	s_sub_u32 s98, s20, 0x4000
	s_subb_u32 s99, s21, 0
	v_lshl_add_u64 v[218:219], s[98:99], 0, v[158:159]
	s_mov_b32 m0, s40
	s_nop 0
	global_load_lds_dwordx4 v[218:219], off
	v_lshl_add_u64 v[218:219], s[20:21], 0, v[164:165]
	s_add_i32 m0, s34, 0xc000
	ds_read_b128 v[186:189], v180
	ds_read_b128 v[190:193], v180 offset:1024
	ds_read_b128 v[194:197], v180 offset:2048
	ds_read_b128 v[198:201], v180 offset:3072
	ds_read_b128 v[202:205], v180 offset:4096
	ds_read_b128 v[206:209], v180 offset:5120
	ds_read_b128 v[210:213], v180 offset:6144
	ds_read_b128 v[214:217], v180 offset:7168
	global_load_lds_dwordx4 v[218:219], off
	v_lshl_add_u64 v[218:219], s[20:21], 0, v[166:167]
	s_add_i32 m0, s34, 0xe000
	s_nop 0
	global_load_lds_dwordx4 v[218:219], off
	s_waitcnt vmcnt(8)
	s_waitcnt lgkmcnt(0)
	s_barrier
	s_setprio 1
	s_waitcnt lgkmcnt(0)
	v_mfma_i32_16x16x64_i8 v[142:145], v[66:69], v[186:189], v[142:145]
	v_mfma_i32_16x16x64_i8 v[138:141], v[74:77], v[186:189], v[138:141]
	v_mfma_i32_16x16x64_i8 v[126:129], v[66:69], v[194:197], v[126:129]
	v_mfma_i32_16x16x64_i8 v[122:125], v[74:77], v[194:197], v[122:125]
	v_mfma_i32_16x16x64_i8 v[110:113], v[66:69], v[202:205], v[110:113]
	v_mfma_i32_16x16x64_i8 v[106:109], v[74:77], v[202:205], v[106:109]
	v_mfma_i32_16x16x64_i8 v[94:97], v[66:69], v[210:213], v[94:97]
	v_mfma_i32_16x16x64_i8 v[90:93], v[74:77], v[210:213], v[90:93]
	v_mfma_i32_16x16x64_i8 v[142:145], v[70:73], v[190:193], v[142:145]
	v_mfma_i32_16x16x64_i8 v[138:141], v[78:81], v[190:193], v[138:141]
	v_mfma_i32_16x16x64_i8 v[126:129], v[70:73], v[198:201], v[126:129]
	v_mfma_i32_16x16x64_i8 v[122:125], v[78:81], v[198:201], v[122:125]
	v_mfma_i32_16x16x64_i8 v[110:113], v[70:73], v[206:209], v[110:113]
	v_mfma_i32_16x16x64_i8 v[106:109], v[78:81], v[206:209], v[106:109]
	v_mfma_i32_16x16x64_i8 v[94:97], v[70:73], v[214:217], v[94:97]
	v_mfma_i32_16x16x64_i8 v[90:93], v[78:81], v[214:217], v[90:93]
	s_setprio 0
	s_setprio 1
	v_mfma_i32_16x16x64_i8 v[134:137], v[146:149], v[186:189], v[134:137]
	v_mfma_i32_16x16x64_i8 v[130:133], v[172:175], v[186:189], v[130:133]
	v_mfma_i32_16x16x64_i8 v[118:121], v[146:149], v[194:197], v[118:121]
	v_mfma_i32_16x16x64_i8 v[114:117], v[172:175], v[194:197], v[114:117]
	v_mfma_i32_16x16x64_i8 v[102:105], v[146:149], v[202:205], v[102:105]
	v_mfma_i32_16x16x64_i8 v[98:101], v[172:175], v[202:205], v[98:101]
	v_mfma_i32_16x16x64_i8 v[86:89], v[146:149], v[210:213], v[86:89]
	v_mfma_i32_16x16x64_i8 v[82:85], v[172:175], v[210:213], v[82:85]
	v_mfma_i32_16x16x64_i8 v[134:137], v[150:153], v[190:193], v[134:137]
	v_mfma_i32_16x16x64_i8 v[130:133], v[182:185], v[190:193], v[130:133]
	v_mfma_i32_16x16x64_i8 v[118:121], v[150:153], v[198:201], v[118:121]
	v_mfma_i32_16x16x64_i8 v[114:117], v[182:185], v[198:201], v[114:117]
	v_mfma_i32_16x16x64_i8 v[102:105], v[150:153], v[206:209], v[102:105]
	v_mfma_i32_16x16x64_i8 v[98:101], v[182:185], v[206:209], v[98:101]
	v_mfma_i32_16x16x64_i8 v[86:89], v[150:153], v[214:217], v[86:89]
	v_mfma_i32_16x16x64_i8 v[82:85], v[182:185], v[214:217], v[82:85]
	s_setprio 0
	s_barrier
	s_add_i32 s52, s43, s33
	v_lshl_add_u64 v[218:219], s[24:25], 0, v[156:157]
	s_mov_b32 m0, s52
	ds_read_b128 v[186:189], v180 offset:16384
	ds_read_b128 v[190:193], v180 offset:17408
	ds_read_b128 v[194:197], v180 offset:18432
	ds_read_b128 v[198:201], v180 offset:19456
	ds_read_b128 v[202:205], v180 offset:20480
	ds_read_b128 v[206:209], v180 offset:21504
	ds_read_b128 v[210:213], v180 offset:22528
	ds_read_b128 v[214:217], v180 offset:23552
	global_load_lds_dwordx4 v[218:219], off
	s_add_i32 m0, s52, 0x2000
	s_add_u32 s52, s24, 0x4000
	v_lshl_add_u64 v[218:219], s[24:25], 0, v[160:161]
	s_addc_u32 s53, s25, 0
	s_add_i32 s54, s44, s33
	global_load_lds_dwordx4 v[218:219], off
	v_lshl_add_u64 v[218:219], s[52:53], 0, v[156:157]
	s_mov_b32 m0, s54
	s_nop 0
	global_load_lds_dwordx4 v[218:219], off
	v_lshl_add_u64 v[218:219], s[52:53], 0, v[160:161]
	s_add_i32 m0, s54, 0x2000
	s_nop 0
	global_load_lds_dwordx4 v[218:219], off
	v_lshl_add_u64 v[218:219], s[26:27], 0, v[154:155]
	s_mov_b32 m0, s34
	s_nop 0
	global_load_lds_dwordx4 v[218:219], off
	s_waitcnt vmcnt(7)
	s_waitcnt lgkmcnt(0)
	s_barrier
; #define PG8_STAGE(bufoff, gbase, voff) do { _Pragma("unroll") for (int _i = 0; _i < 2; ++_i) \
;         __builtin_amdgcn_global_load_lds((const unsigned*)((const char*)(gbase) + (voff)[_i]), (LAS unsigned*)(lds + (bufoff) + ldsw + _i * 8192), 16, 0, 0); } while (0)
; #define PG8_LDA(dst, b, h) do { _Pragma("unroll") for (int m = 0; m < 4; ++m) _Pragma("unroll") for (int k = 0; k < 2; ++k) dst[m][k] = *(const LAS bf16x8*)(lds + PG8_SA(b, h) + aoff + m * 2048 + k * 1024); } while (0)
; #define PG8_LDB(dst, b, h) do { _Pragma("unroll") for (int n = 0; n < 2; ++n) _Pragma("unroll") for (int k = 0; k < 2; ++k) dst[n][k] = *(const LAS bf16x8*)(lds + PG8_SB(b, h) + boff + n * 2048 + k * 1024); } while (0)
; #define PG8_WAIT_V(n) asm volatile("s_waitcnt vmcnt(" #n ")" ::: "memory")
; #define PG8_WAIT_L(n) asm volatile("s_waitcnt lgkmcnt(" #n ")" ::: "memory")
; #define PG8_BAR __builtin_amdgcn_s_barrier()
; #define PG8_SCHED __builtin_amdgcn_sched_barrier(0)
; template <class Epi, class Sched, bool I8 = false>
; __device__ __forceinline__ void gemm_phase(LAS unsigned char* lds, const Gemm g, const Sched& S, const Epi& E) {
;     ...
;             PG8_WAIT_V(8); PG8_WAIT_L(0); PG8_BAR; PG8_MMA(1, 0, At, B0); PG8_MMA(1, 1, At, B1); PG8_BAR; PG8_SCHED;
;             PG8_LDB(B0, 1, 0); PG8_LDB(B1, 1, 1); PG8_SCHED; PG8_LDA(At, 1, 0); PG8_STAGE(PG8_SA(0, 1), a2 + hstepA, voffA);
;             PG8_WAIT_V(8); PG8_WAIT_L(0); PG8_BAR; PG8_MMA(0, 0, At, B0); PG8_MMA(0, 1, At, B1); PG8_BAR; PG8_SCHED;
	s_setprio 1
	s_waitcnt lgkmcnt(0)
	v_mfma_i32_16x16x64_i8 v[62:65], v[66:69], v[186:189], v[62:65]
	v_mfma_i32_16x16x64_i8 v[58:61], v[74:77], v[186:189], v[58:61]
	v_mfma_i32_16x16x64_i8 v[46:49], v[66:69], v[194:197], v[46:49]
	v_mfma_i32_16x16x64_i8 v[42:45], v[74:77], v[194:197], v[42:45]
	v_mfma_i32_16x16x64_i8 v[30:33], v[66:69], v[202:205], v[30:33]
	v_mfma_i32_16x16x64_i8 v[26:29], v[74:77], v[202:205], v[26:29]
	v_mfma_i32_16x16x64_i8 v[14:17], v[66:69], v[210:213], v[14:17]
	v_mfma_i32_16x16x64_i8 v[10:13], v[74:77], v[210:213], v[10:13]
	v_mfma_i32_16x16x64_i8 v[62:65], v[70:73], v[190:193], v[62:65]
	v_mfma_i32_16x16x64_i8 v[58:61], v[78:81], v[190:193], v[58:61]
	v_mfma_i32_16x16x64_i8 v[46:49], v[70:73], v[198:201], v[46:49]
	v_mfma_i32_16x16x64_i8 v[42:45], v[78:81], v[198:201], v[42:45]
	v_mfma_i32_16x16x64_i8 v[30:33], v[70:73], v[206:209], v[30:33]
	v_mfma_i32_16x16x64_i8 v[26:29], v[78:81], v[206:209], v[26:29]
	v_mfma_i32_16x16x64_i8 v[14:17], v[70:73], v[214:217], v[14:17]
	v_mfma_i32_16x16x64_i8 v[10:13], v[78:81], v[214:217], v[10:13]
	s_setprio 0
	s_setprio 1
	v_mfma_i32_16x16x64_i8 v[54:57], v[146:149], v[186:189], v[54:57]
	v_mfma_i32_16x16x64_i8 v[50:53], v[172:175], v[186:189], v[50:53]
	v_mfma_i32_16x16x64_i8 v[38:41], v[146:149], v[194:197], v[38:41]
	v_mfma_i32_16x16x64_i8 v[34:37], v[172:175], v[194:197], v[34:37]
	v_mfma_i32_16x16x64_i8 v[22:25], v[146:149], v[202:205], v[22:25]
	v_mfma_i32_16x16x64_i8 v[18:21], v[172:175], v[202:205], v[18:21]
	v_mfma_i32_16x16x64_i8 v[6:9], v[146:149], v[210:213], v[6:9]
	v_mfma_i32_16x16x64_i8 v[2:5], v[172:175], v[210:213], v[2:5]
	v_mfma_i32_16x16x64_i8 v[54:57], v[150:153], v[190:193], v[54:57]
	v_mfma_i32_16x16x64_i8 v[50:53], v[182:185], v[190:193], v[50:53]
	v_mfma_i32_16x16x64_i8 v[38:41], v[150:153], v[198:201], v[38:41]
	v_mfma_i32_16x16x64_i8 v[34:37], v[182:185], v[198:201], v[34:37]
	v_mfma_i32_16x16x64_i8 v[22:25], v[150:153], v[206:209], v[22:25]
	v_mfma_i32_16x16x64_i8 v[18:21], v[182:185], v[206:209], v[18:21]
	v_mfma_i32_16x16x64_i8 v[6:9], v[150:153], v[214:217], v[6:9]
	v_mfma_i32_16x16x64_i8 v[2:5], v[182:185], v[214:217], v[2:5]
	s_setprio 0
	s_barrier
	s_add_i32 s52, 0, 0x18000
	s_add_i32 s53, 0, 0x1c000
	v_add_u32_e32 v78, s52, v176
	v_add_u32_e32 v162, s53, v176
	ds_read_b128 v[66:69], v78
	ds_read_b128 v[70:73], v78 offset:1024
	ds_read_b128 v[74:77], v78 offset:2048
	ds_read_b128 v[78:81], v78 offset:3072
	ds_read_b128 v[146:149], v162
	ds_read_b128 v[150:153], v162 offset:1024
	ds_read_b128 v[172:175], v162 offset:2048
	ds_read_b128 v[182:185], v162 offset:3072
	v_lshl_add_u64 v[218:219], s[26:27], 0, v[158:159]
	s_mov_b32 m0, s35
	s_nop 0
	global_load_lds_dwordx4 v[218:219], off
	s_add_u32 s26, s26, 0x4000
	s_addc_u32 s27, s27, 0
	s_mov_b32 m0, s36
	v_lshl_add_u64 v[218:219], s[26:27], 0, v[154:155]
	ds_read_b128 v[186:189], v180 offset:32768
	ds_read_b128 v[190:193], v180 offset:33792
	ds_read_b128 v[194:197], v180 offset:34816
	ds_read_b128 v[198:201], v180 offset:35840
	ds_read_b128 v[202:205], v180 offset:36864
	ds_read_b128 v[206:209], v180 offset:37888
	ds_read_b128 v[210:213], v180 offset:38912
	ds_read_b128 v[214:217], v180 offset:39936
	global_load_lds_dwordx4 v[218:219], off
	v_lshl_add_u64 v[218:219], s[26:27], 0, v[158:159]
	s_mov_b32 m0, s37
	s_nop 0
	global_load_lds_dwordx4 v[218:219], off
	s_waitcnt vmcnt(8)
	s_waitcnt lgkmcnt(0)
	s_barrier
	s_setprio 1
	s_waitcnt lgkmcnt(0)
	v_mfma_i32_16x16x64_i8 v[142:145], v[66:69], v[186:189], v[142:145]
	v_mfma_i32_16x16x64_i8 v[138:141], v[74:77], v[186:189], v[138:141]
	v_mfma_i32_16x16x64_i8 v[126:129], v[66:69], v[194:197], v[126:129]
	v_mfma_i32_16x16x64_i8 v[122:125], v[74:77], v[194:197], v[122:125]
	v_mfma_i32_16x16x64_i8 v[110:113], v[66:69], v[202:205], v[110:113]
	v_mfma_i32_16x16x64_i8 v[106:109], v[74:77], v[202:205], v[106:109]
	v_mfma_i32_16x16x64_i8 v[94:97], v[66:69], v[210:213], v[94:97]
	v_mfma_i32_16x16x64_i8 v[90:93], v[74:77], v[210:213], v[90:93]
	v_mfma_i32_16x16x64_i8 v[142:145], v[70:73], v[190:193], v[142:145]
	v_mfma_i32_16x16x64_i8 v[138:141], v[78:81], v[190:193], v[138:141]
	v_mfma_i32_16x16x64_i8 v[126:129], v[70:73], v[198:201], v[126:129]
	v_mfma_i32_16x16x64_i8 v[122:125], v[78:81], v[198:201], v[122:125]
	v_mfma_i32_16x16x64_i8 v[110:113], v[70:73], v[206:209], v[110:113]
	v_mfma_i32_16x16x64_i8 v[106:109], v[78:81], v[206:209], v[106:109]
	v_mfma_i32_16x16x64_i8 v[94:97], v[70:73], v[214:217], v[94:97]
	v_mfma_i32_16x16x64_i8 v[90:93], v[78:81], v[214:217], v[90:93]
	s_setprio 0
	s_setprio 1
	v_mfma_i32_16x16x64_i8 v[134:137], v[146:149], v[186:189], v[134:137]
	v_mfma_i32_16x16x64_i8 v[130:133], v[172:175], v[186:189], v[130:133]
	v_mfma_i32_16x16x64_i8 v[118:121], v[146:149], v[194:197], v[118:121]
	v_mfma_i32_16x16x64_i8 v[114:117], v[172:175], v[194:197], v[114:117]
	v_mfma_i32_16x16x64_i8 v[102:105], v[146:149], v[202:205], v[102:105]
	v_mfma_i32_16x16x64_i8 v[98:101], v[172:175], v[202:205], v[98:101]
	v_mfma_i32_16x16x64_i8 v[86:89], v[146:149], v[210:213], v[86:89]
	v_mfma_i32_16x16x64_i8 v[82:85], v[172:175], v[210:213], v[82:85]
	v_mfma_i32_16x16x64_i8 v[134:137], v[150:153], v[190:193], v[134:137]
	v_mfma_i32_16x16x64_i8 v[130:133], v[182:185], v[190:193], v[130:133]
	v_mfma_i32_16x16x64_i8 v[118:121], v[150:153], v[198:201], v[118:121]
	v_mfma_i32_16x16x64_i8 v[114:117], v[182:185], v[198:201], v[114:117]
	v_mfma_i32_16x16x64_i8 v[102:105], v[150:153], v[206:209], v[102:105]
	v_mfma_i32_16x16x64_i8 v[98:101], v[182:185], v[206:209], v[98:101]
	v_mfma_i32_16x16x64_i8 v[86:89], v[150:153], v[214:217], v[86:89]
	v_mfma_i32_16x16x64_i8 v[82:85], v[182:185], v[214:217], v[82:85]
	s_setprio 0
	s_barrier
; #define PG8_STAGE(bufoff, gbase, voff) do { _Pragma("unroll") for (int _i = 0; _i < 2; ++_i) \
;         __builtin_amdgcn_global_load_lds((const unsigned*)((const char*)(gbase) + (voff)[_i]), (LAS unsigned*)(lds + (bufoff) + ldsw + _i * 8192), 16, 0, 0); } while (0)
; #define PG8_LDA(dst, b, h) do { _Pragma("unroll") for (int m = 0; m < 4; ++m) _Pragma("unroll") for (int k = 0; k < 2; ++k) dst[m][k] = *(const LAS bf16x8*)(lds + PG8_SA(b, h) + aoff + m * 2048 + k * 1024); } while (0)
; #define PG8_WAIT_V(n) asm volatile("s_waitcnt vmcnt(" #n ")" ::: "memory")
; #define PG8_WAIT_L(n) asm volatile("s_waitcnt lgkmcnt(" #n ")" ::: "memory")
; #define PG8_BAR __builtin_amdgcn_s_barrier()
; #define PG8_SCHED __builtin_amdgcn_sched_barrier(0)
; template <class Epi, class Sched, bool I8 = false>
; __device__ __forceinline__ void gemm_phase(LAS unsigned char* lds, const Gemm g, const Sched& S, const Epi& E) {
;     ...
;             PG8_LDA(At, 1, 1); PG8_STAGE(PG8_SB(1, 0), b3, voffB); PG8_STAGE(PG8_SB(1, 1), b3 + hstepB, voffB); PG8_STAGE(PG8_SA(1, 0), a3, voffA);
;             PG8_WAIT_V(8); PG8_WAIT_L(0); PG8_BAR; PG8_MMA(1, 0, At, B0); PG8_MMA(1, 1, At, B1); PG8_BAR; PG8_SCHED;
;         }
	s_add_u32 s26, s24, 0x8000
	s_addc_u32 s27, s25, 0
	s_add_i32 s52, s52, s33
	v_lshl_add_u64 v[218:219], s[26:27], 0, v[156:157]
	s_mov_b32 m0, s52
	ds_read_b128 v[186:189], v180 offset:49152
	ds_read_b128 v[190:193], v180 offset:50176
	ds_read_b128 v[194:197], v180 offset:51200
	ds_read_b128 v[198:201], v180 offset:52224
	ds_read_b128 v[202:205], v180 offset:53248
	ds_read_b128 v[206:209], v180 offset:54272
	ds_read_b128 v[210:213], v180 offset:55296
	ds_read_b128 v[214:217], v180 offset:56320
	global_load_lds_dwordx4 v[218:219], off
	s_add_i32 m0, s52, 0x2000
	s_add_u32 s24, s24, 0xc000
	v_lshl_add_u64 v[218:219], s[26:27], 0, v[160:161]
	s_addc_u32 s25, s25, 0
	s_add_i32 s26, s53, s33
	global_load_lds_dwordx4 v[218:219], off
	v_lshl_add_u64 v[218:219], s[24:25], 0, v[156:157]
	s_mov_b32 m0, s26
	s_nop 0
	global_load_lds_dwordx4 v[218:219], off
	v_lshl_add_u64 v[218:219], s[24:25], 0, v[160:161]
	s_add_i32 m0, s26, 0x2000
	s_nop 0
	global_load_lds_dwordx4 v[218:219], off
	v_lshl_add_u64 v[218:219], s[22:23], 0, v[154:155]
	s_mov_b32 m0, s39
	s_nop 0
	global_load_lds_dwordx4 v[218:219], off
	s_waitcnt vmcnt(7)
	s_waitcnt lgkmcnt(0)
	s_barrier
	s_setprio 1
	s_waitcnt lgkmcnt(0)
	v_mfma_i32_16x16x64_i8 v[62:65], v[66:69], v[186:189], v[62:65]
	v_mfma_i32_16x16x64_i8 v[58:61], v[74:77], v[186:189], v[58:61]
	v_mfma_i32_16x16x64_i8 v[46:49], v[66:69], v[194:197], v[46:49]
	v_mfma_i32_16x16x64_i8 v[42:45], v[74:77], v[194:197], v[42:45]
	v_mfma_i32_16x16x64_i8 v[30:33], v[66:69], v[202:205], v[30:33]
	v_mfma_i32_16x16x64_i8 v[26:29], v[74:77], v[202:205], v[26:29]
	v_mfma_i32_16x16x64_i8 v[14:17], v[66:69], v[210:213], v[14:17]
	v_mfma_i32_16x16x64_i8 v[10:13], v[74:77], v[210:213], v[10:13]
	v_mfma_i32_16x16x64_i8 v[62:65], v[70:73], v[190:193], v[62:65]
	v_mfma_i32_16x16x64_i8 v[58:61], v[78:81], v[190:193], v[58:61]
	v_mfma_i32_16x16x64_i8 v[46:49], v[70:73], v[198:201], v[46:49]
	v_mfma_i32_16x16x64_i8 v[42:45], v[78:81], v[198:201], v[42:45]
	v_mfma_i32_16x16x64_i8 v[30:33], v[70:73], v[206:209], v[30:33]
	v_mfma_i32_16x16x64_i8 v[26:29], v[78:81], v[206:209], v[26:29]
	v_mfma_i32_16x16x64_i8 v[14:17], v[70:73], v[214:217], v[14:17]
	v_mfma_i32_16x16x64_i8 v[10:13], v[78:81], v[214:217], v[10:13]
	s_setprio 0
	s_setprio 1
	v_mfma_i32_16x16x64_i8 v[54:57], v[146:149], v[186:189], v[54:57]
	v_mfma_i32_16x16x64_i8 v[50:53], v[172:175], v[186:189], v[50:53]
	v_mfma_i32_16x16x64_i8 v[38:41], v[146:149], v[194:197], v[38:41]
	v_mfma_i32_16x16x64_i8 v[34:37], v[172:175], v[194:197], v[34:37]
	v_mfma_i32_16x16x64_i8 v[22:25], v[146:149], v[202:205], v[22:25]
	v_mfma_i32_16x16x64_i8 v[18:21], v[172:175], v[202:205], v[18:21]
	v_mfma_i32_16x16x64_i8 v[6:9], v[146:149], v[210:213], v[6:9]
	v_mfma_i32_16x16x64_i8 v[2:5], v[172:175], v[210:213], v[2:5]
	v_mfma_i32_16x16x64_i8 v[54:57], v[150:153], v[190:193], v[54:57]
	v_mfma_i32_16x16x64_i8 v[50:53], v[182:185], v[190:193], v[50:53]
	v_mfma_i32_16x16x64_i8 v[38:41], v[150:153], v[198:201], v[38:41]
	v_mfma_i32_16x16x64_i8 v[34:37], v[182:185], v[198:201], v[34:37]
	v_mfma_i32_16x16x64_i8 v[22:25], v[150:153], v[206:209], v[22:25]
	v_mfma_i32_16x16x64_i8 v[18:21], v[182:185], v[206:209], v[18:21]
	v_mfma_i32_16x16x64_i8 v[6:9], v[150:153], v[214:217], v[6:9]
	v_mfma_i32_16x16x64_i8 v[2:5], v[182:185], v[214:217], v[2:5]
	s_setprio 0
	s_barrier
	s_add_i32 s51, s51, 2
	s_add_u32 s20, s20, 0x10000
	s_addc_u32 s21, s21, 0
	s_add_u32 s49, s49, 0x10000
	s_addc_u32 s50, s50, 0
	s_cmpk_gt_u32 s51, 0x53
	s_cbranch_scc0 .LBB0_4168
	s_and_b64 vcc, exec, s[14:15]
	s_cbranch_vccz .LBB0_4171
	s_barrier
